# wave-half priority asymmetry kept after the GEMMs (no reset at GEMM exit), so the following LayerNorm, conv, prep and post phases run with waves 0-3 at priority 1
# baseline (speedup 1.0000x reference)
.LBB0_115:
	s_add_u32 s14, s12, 0x100
	s_addc_u32 s15, s13, 0
	s_add_i32 s45, 0, 0x10000
	v_add_u32_e32 v148, s45, v141
	ds_read_b128 v[144:147], v148
	ds_read_b128 v[160:163], v148 offset:1024
	ds_read_b128 v[164:167], v148 offset:2048
	ds_read_b128 v[168:171], v148 offset:3072
	s_cmp_eq_u32 s44, 40
	s_cselect_b32 s23, s9, s15
	s_cselect_b32 s22, s8, s14
	s_cselect_b32 s19, s11, s43
	s_cselect_b32 s18, s10, s42
	v_lshl_add_u64 v[148:149], s[12:13], 0, v[138:139]
	s_add_i32 m0, s30, 0xc000
	ds_read_b128 v[172:175], v143
	ds_read_b128 v[176:179], v143 offset:1024
	ds_read_b128 v[180:183], v143 offset:2048
	ds_read_b128 v[184:187], v143 offset:3072
	ds_read_b128 v[188:191], v143 offset:4096
	ds_read_b128 v[192:195], v143 offset:5120
	ds_read_b128 v[196:199], v143 offset:6144
	ds_read_b128 v[200:203], v143 offset:7168
	global_load_lds_dwordx4 v[148:149], off
	v_lshl_add_u64 v[148:149], s[12:13], 0, v[136:137]
	s_add_i32 m0, s30, 0xe000
	s_nop 0
	global_load_lds_dwordx4 v[148:149], off
	s_waitcnt lgkmcnt(8)
	s_barrier
	s_waitcnt lgkmcnt(0)
	s_waitcnt lgkmcnt(0)
	v_mfma_f32_16x16x32_bf16 v[126:129], v[144:147], v[172:175], v[126:129]
	v_mfma_f32_16x16x32_bf16 v[122:125], v[164:167], v[172:175], v[122:125]
	v_mfma_f32_16x16x32_bf16 v[118:121], v[144:147], v[180:183], v[118:121]
	v_mfma_f32_16x16x32_bf16 v[114:117], v[164:167], v[180:183], v[114:117]
	v_mfma_f32_16x16x32_bf16 v[102:105], v[144:147], v[188:191], v[102:105]
	v_mfma_f32_16x16x32_bf16 v[98:101], v[164:167], v[188:191], v[98:101]
	v_mfma_f32_16x16x32_bf16 v[86:89], v[144:147], v[196:199], v[86:89]
	v_mfma_f32_16x16x32_bf16 v[82:85], v[164:167], v[196:199], v[82:85]
	v_mfma_f32_16x16x32_bf16 v[126:129], v[160:163], v[176:179], v[126:129]
	v_mfma_f32_16x16x32_bf16 v[122:125], v[168:171], v[176:179], v[122:125]
	v_mfma_f32_16x16x32_bf16 v[118:121], v[160:163], v[184:187], v[118:121]
	v_mfma_f32_16x16x32_bf16 v[114:117], v[168:171], v[184:187], v[114:117]
	v_mfma_f32_16x16x32_bf16 v[102:105], v[160:163], v[192:195], v[102:105]
	v_mfma_f32_16x16x32_bf16 v[98:101], v[168:171], v[192:195], v[98:101]
	v_mfma_f32_16x16x32_bf16 v[86:89], v[160:163], v[200:203], v[86:89]
	v_mfma_f32_16x16x32_bf16 v[82:85], v[168:171], v[200:203], v[82:85]
	s_barrier
	s_add_i32 s52, 0, 0x14000
	v_add_u32_e32 v148, s52, v141
	s_add_i32 s12, s45, s29
	ds_read_b128 v[234:237], v148
	ds_read_b128 v[238:241], v148 offset:1024
	ds_read_b128 v[242:245], v148 offset:2048
	ds_read_b128 v[246:249], v148 offset:3072
	v_lshl_add_u64 v[148:149], s[18:19], 0, v[0:1]
	s_mov_b32 m0, s12
	v_lshl_add_u64 v[204:205], s[18:19], 0, v[134:135]
	global_load_lds_dwordx4 v[148:149], off
	s_add_i32 m0, s12, 0x2000
	s_nop 0
	global_load_lds_dwordx4 v[204:205], off
	s_barrier
	s_waitcnt lgkmcnt(0)
	s_waitcnt lgkmcnt(0)
	v_mfma_f32_16x16x32_bf16 v[110:113], v[234:237], v[172:175], v[110:113]
	v_mfma_f32_16x16x32_bf16 v[106:109], v[242:245], v[172:175], v[106:109]
	v_mfma_f32_16x16x32_bf16 v[94:97], v[234:237], v[180:183], v[94:97]
	v_mfma_f32_16x16x32_bf16 v[90:93], v[242:245], v[180:183], v[90:93]
	v_mfma_f32_16x16x32_bf16 v[78:81], v[234:237], v[188:191], v[78:81]
	v_mfma_f32_16x16x32_bf16 v[74:77], v[242:245], v[188:191], v[74:77]
	v_mfma_f32_16x16x32_bf16 v[70:73], v[234:237], v[196:199], v[70:73]
	v_mfma_f32_16x16x32_bf16 v[66:69], v[242:245], v[196:199], v[66:69]
	v_mfma_f32_16x16x32_bf16 v[110:113], v[238:241], v[176:179], v[110:113]
	v_mfma_f32_16x16x32_bf16 v[106:109], v[246:249], v[176:179], v[106:109]
	v_mfma_f32_16x16x32_bf16 v[94:97], v[238:241], v[184:187], v[94:97]
	v_mfma_f32_16x16x32_bf16 v[90:93], v[246:249], v[184:187], v[90:93]
	v_mfma_f32_16x16x32_bf16 v[78:81], v[238:241], v[192:195], v[78:81]
	v_mfma_f32_16x16x32_bf16 v[74:77], v[246:249], v[192:195], v[74:77]
	v_mfma_f32_16x16x32_bf16 v[70:73], v[238:241], v[200:203], v[70:73]
	v_mfma_f32_16x16x32_bf16 v[66:69], v[246:249], v[200:203], v[66:69]
	s_mov_b32 m0, s30
	v_lshl_add_u64 v[250:251], s[22:23], 0, v[130:131]
	s_barrier
	ds_read_b128 v[172:175], v143 offset:16384
	ds_read_b128 v[176:179], v143 offset:17408
	ds_read_b128 v[180:183], v143 offset:18432
	ds_read_b128 v[184:187], v143 offset:19456
	ds_read_b128 v[188:191], v143 offset:20480
	ds_read_b128 v[192:195], v143 offset:21504
	ds_read_b128 v[196:199], v143 offset:22528
	ds_read_b128 v[200:203], v143 offset:23552
	global_load_lds_dwordx4 v[250:251], off
	v_lshl_add_u64 v[252:253], s[22:23], 0, v[132:133]
	s_mov_b32 m0, s31
	s_nop 0
	global_load_lds_dwordx4 v[252:253], off
	s_barrier
	s_waitcnt lgkmcnt(0)
	s_waitcnt lgkmcnt(0)
	v_mfma_f32_16x16x32_bf16 v[62:65], v[144:147], v[172:175], v[62:65]
	v_mfma_f32_16x16x32_bf16 v[58:61], v[164:167], v[172:175], v[58:61]
	v_mfma_f32_16x16x32_bf16 v[54:57], v[144:147], v[180:183], v[54:57]
	v_mfma_f32_16x16x32_bf16 v[50:53], v[164:167], v[180:183], v[50:53]
	v_mfma_f32_16x16x32_bf16 v[38:41], v[144:147], v[188:191], v[38:41]
	v_mfma_f32_16x16x32_bf16 v[34:37], v[164:167], v[188:191], v[34:37]
	v_mfma_f32_16x16x32_bf16 v[22:25], v[144:147], v[196:199], v[22:25]
	v_mfma_f32_16x16x32_bf16 v[18:21], v[164:167], v[196:199], v[18:21]
	v_mfma_f32_16x16x32_bf16 v[62:65], v[160:163], v[176:179], v[62:65]
	v_mfma_f32_16x16x32_bf16 v[58:61], v[168:171], v[176:179], v[58:61]
	v_mfma_f32_16x16x32_bf16 v[54:57], v[160:163], v[184:187], v[54:57]
	v_mfma_f32_16x16x32_bf16 v[50:53], v[168:171], v[184:187], v[50:53]
	v_mfma_f32_16x16x32_bf16 v[38:41], v[160:163], v[192:195], v[38:41]
	v_mfma_f32_16x16x32_bf16 v[34:37], v[168:171], v[192:195], v[34:37]
	v_mfma_f32_16x16x32_bf16 v[22:25], v[160:163], v[200:203], v[22:25]
	v_mfma_f32_16x16x32_bf16 v[18:21], v[168:171], v[200:203], v[18:21]
	s_barrier
	s_add_u32 s12, s18, 0xb0000
	s_addc_u32 s13, s19, 0
	s_add_i32 s45, s52, s29
	v_lshl_add_u64 v[144:145], s[12:13], 0, v[0:1]
	s_mov_b32 m0, s45
	s_nop 0
	global_load_lds_dwordx4 v[144:145], off
	v_lshl_add_u64 v[144:145], s[12:13], 0, v[134:135]
	s_add_i32 m0, s45, 0x2000
	s_nop 0
	global_load_lds_dwordx4 v[144:145], off
	s_waitcnt vmcnt(6)
	s_barrier
	v_mfma_f32_16x16x32_bf16 v[46:49], v[234:237], v[172:175], v[46:49]
	v_mfma_f32_16x16x32_bf16 v[42:45], v[242:245], v[172:175], v[42:45]
	v_mfma_f32_16x16x32_bf16 v[30:33], v[234:237], v[180:183], v[30:33]
	v_mfma_f32_16x16x32_bf16 v[26:29], v[242:245], v[180:183], v[26:29]
	v_mfma_f32_16x16x32_bf16 v[14:17], v[234:237], v[188:191], v[14:17]
	v_mfma_f32_16x16x32_bf16 v[10:13], v[242:245], v[188:191], v[10:13]
	v_mfma_f32_16x16x32_bf16 v[6:9], v[234:237], v[196:199], v[6:9]
	v_mfma_f32_16x16x32_bf16 v[2:5], v[242:245], v[196:199], v[2:5]
	v_mfma_f32_16x16x32_bf16 v[46:49], v[238:241], v[176:179], v[46:49]
	v_mfma_f32_16x16x32_bf16 v[42:45], v[246:249], v[176:179], v[42:45]
	v_mfma_f32_16x16x32_bf16 v[30:33], v[238:241], v[184:187], v[30:33]
	v_mfma_f32_16x16x32_bf16 v[26:29], v[246:249], v[184:187], v[26:29]
	v_mfma_f32_16x16x32_bf16 v[14:17], v[238:241], v[192:195], v[14:17]
	v_mfma_f32_16x16x32_bf16 v[10:13], v[246:249], v[192:195], v[10:13]
	v_mfma_f32_16x16x32_bf16 v[6:9], v[238:241], v[200:203], v[6:9]
	v_mfma_f32_16x16x32_bf16 v[2:5], v[246:249], v[200:203], v[2:5]
	s_add_i32 s45, 0, 0x18000
	v_add_u32_e32 v159, s45, v141
	s_barrier
	ds_read_b128 v[144:147], v159
	ds_read_b128 v[160:163], v159 offset:1024
	ds_read_b128 v[164:167], v159 offset:2048
	ds_read_b128 v[168:171], v159 offset:3072
	s_add_u32 s12, s22, 0xb0000
	s_addc_u32 s13, s23, 0
	s_mov_b32 m0, s34
	v_lshl_add_u64 v[234:235], s[12:13], 0, v[130:131]
	ds_read_b128 v[172:175], v143 offset:32768
	ds_read_b128 v[176:179], v143 offset:33792
	ds_read_b128 v[180:183], v143 offset:34816
	ds_read_b128 v[184:187], v143 offset:35840
	ds_read_b128 v[188:191], v143 offset:36864
	ds_read_b128 v[192:195], v143 offset:37888
	ds_read_b128 v[196:199], v143 offset:38912
	ds_read_b128 v[200:203], v143 offset:39936
	global_load_lds_dwordx4 v[234:235], off
	v_lshl_add_u64 v[234:235], s[12:13], 0, v[132:133]
	s_mov_b32 m0, s35
	s_nop 0
	global_load_lds_dwordx4 v[234:235], off
	s_waitcnt lgkmcnt(8)
	s_barrier
	s_waitcnt lgkmcnt(0)
	s_waitcnt lgkmcnt(0)
	v_mfma_f32_16x16x32_bf16 v[126:129], v[144:147], v[172:175], v[126:129]
	v_mfma_f32_16x16x32_bf16 v[122:125], v[164:167], v[172:175], v[122:125]
	v_mfma_f32_16x16x32_bf16 v[118:121], v[144:147], v[180:183], v[118:121]
	v_mfma_f32_16x16x32_bf16 v[114:117], v[164:167], v[180:183], v[114:117]
	v_mfma_f32_16x16x32_bf16 v[102:105], v[144:147], v[188:191], v[102:105]
	v_mfma_f32_16x16x32_bf16 v[98:101], v[164:167], v[188:191], v[98:101]
	v_mfma_f32_16x16x32_bf16 v[86:89], v[144:147], v[196:199], v[86:89]
	v_mfma_f32_16x16x32_bf16 v[82:85], v[164:167], v[196:199], v[82:85]
	v_mfma_f32_16x16x32_bf16 v[126:129], v[160:163], v[176:179], v[126:129]
	v_mfma_f32_16x16x32_bf16 v[122:125], v[168:171], v[176:179], v[122:125]
	v_mfma_f32_16x16x32_bf16 v[118:121], v[160:163], v[184:187], v[118:121]
	v_mfma_f32_16x16x32_bf16 v[114:117], v[168:171], v[184:187], v[114:117]
	v_mfma_f32_16x16x32_bf16 v[102:105], v[160:163], v[192:195], v[102:105]
	v_mfma_f32_16x16x32_bf16 v[98:101], v[168:171], v[192:195], v[98:101]
	v_mfma_f32_16x16x32_bf16 v[86:89], v[160:163], v[200:203], v[86:89]
	v_mfma_f32_16x16x32_bf16 v[82:85], v[168:171], v[200:203], v[82:85]
	s_barrier
	s_add_i32 s22, 0, 0x1c000
	s_add_i32 s12, s45, s29
	v_add_u32_e32 v159, s22, v141
	v_lshl_add_u64 v[148:149], v[148:149], 0, s[20:21]
	s_mov_b32 m0, s12
	ds_read_b128 v[234:237], v159
	ds_read_b128 v[238:241], v159 offset:1024
	ds_read_b128 v[242:245], v159 offset:2048
	ds_read_b128 v[246:249], v159 offset:3072
	global_load_lds_dwordx4 v[148:149], off
	v_lshl_add_u64 v[148:149], v[204:205], 0, s[20:21]
	s_add_i32 m0, s12, 0x2000
	s_nop 0
	global_load_lds_dwordx4 v[148:149], off
	s_barrier
	s_waitcnt lgkmcnt(0)
	s_waitcnt lgkmcnt(0)
	v_mfma_f32_16x16x32_bf16 v[110:113], v[234:237], v[172:175], v[110:113]
	v_mfma_f32_16x16x32_bf16 v[106:109], v[242:245], v[172:175], v[106:109]
	v_mfma_f32_16x16x32_bf16 v[94:97], v[234:237], v[180:183], v[94:97]
	v_mfma_f32_16x16x32_bf16 v[90:93], v[242:245], v[180:183], v[90:93]
	v_mfma_f32_16x16x32_bf16 v[78:81], v[234:237], v[188:191], v[78:81]
	v_mfma_f32_16x16x32_bf16 v[74:77], v[242:245], v[188:191], v[74:77]
	v_mfma_f32_16x16x32_bf16 v[70:73], v[234:237], v[196:199], v[70:73]
	v_mfma_f32_16x16x32_bf16 v[66:69], v[242:245], v[196:199], v[66:69]
	v_mfma_f32_16x16x32_bf16 v[110:113], v[238:241], v[176:179], v[110:113]
	v_mfma_f32_16x16x32_bf16 v[106:109], v[246:249], v[176:179], v[106:109]
	v_mfma_f32_16x16x32_bf16 v[94:97], v[238:241], v[184:187], v[94:97]
	v_mfma_f32_16x16x32_bf16 v[90:93], v[246:249], v[184:187], v[90:93]
	v_mfma_f32_16x16x32_bf16 v[78:81], v[238:241], v[192:195], v[78:81]
	v_mfma_f32_16x16x32_bf16 v[74:77], v[246:249], v[192:195], v[74:77]
	v_mfma_f32_16x16x32_bf16 v[70:73], v[238:241], v[200:203], v[70:73]
	v_mfma_f32_16x16x32_bf16 v[66:69], v[246:249], v[200:203], v[66:69]
	s_mov_b32 m0, s38
	v_lshl_add_u64 v[148:149], v[250:251], 0, s[20:21]
	s_barrier
	ds_read_b128 v[172:175], v143 offset:49152
	ds_read_b128 v[176:179], v143 offset:50176
	ds_read_b128 v[180:183], v143 offset:51200
	ds_read_b128 v[184:187], v143 offset:52224
	ds_read_b128 v[188:191], v143 offset:53248
	ds_read_b128 v[192:195], v143 offset:54272
	ds_read_b128 v[196:199], v143 offset:55296
	ds_read_b128 v[200:203], v143 offset:56320
	global_load_lds_dwordx4 v[148:149], off
	v_lshl_add_u64 v[148:149], v[252:253], 0, s[20:21]
	s_mov_b32 m0, s39
	s_nop 0
	global_load_lds_dwordx4 v[148:149], off
	s_barrier
	s_waitcnt lgkmcnt(0)
	s_waitcnt lgkmcnt(0)
	v_mfma_f32_16x16x32_bf16 v[62:65], v[144:147], v[172:175], v[62:65]
	v_mfma_f32_16x16x32_bf16 v[58:61], v[164:167], v[172:175], v[58:61]
	v_mfma_f32_16x16x32_bf16 v[54:57], v[144:147], v[180:183], v[54:57]
	v_mfma_f32_16x16x32_bf16 v[50:53], v[164:167], v[180:183], v[50:53]
	v_mfma_f32_16x16x32_bf16 v[38:41], v[144:147], v[188:191], v[38:41]
	v_mfma_f32_16x16x32_bf16 v[34:37], v[164:167], v[188:191], v[34:37]
	v_mfma_f32_16x16x32_bf16 v[22:25], v[144:147], v[196:199], v[22:25]
	v_mfma_f32_16x16x32_bf16 v[18:21], v[164:167], v[196:199], v[18:21]
	v_mfma_f32_16x16x32_bf16 v[62:65], v[160:163], v[176:179], v[62:65]
	v_mfma_f32_16x16x32_bf16 v[58:61], v[168:171], v[176:179], v[58:61]
	v_mfma_f32_16x16x32_bf16 v[54:57], v[160:163], v[184:187], v[54:57]
	v_mfma_f32_16x16x32_bf16 v[50:53], v[168:171], v[184:187], v[50:53]
	v_mfma_f32_16x16x32_bf16 v[38:41], v[160:163], v[192:195], v[38:41]
	v_mfma_f32_16x16x32_bf16 v[34:37], v[168:171], v[192:195], v[34:37]
	v_mfma_f32_16x16x32_bf16 v[22:25], v[160:163], v[200:203], v[22:25]
	v_mfma_f32_16x16x32_bf16 v[18:21], v[168:171], v[200:203], v[18:21]
	s_barrier
	s_add_u32 s12, s18, 0xb0080
	s_addc_u32 s13, s19, 0
	s_add_i32 s18, s22, s29
	v_lshl_add_u64 v[144:145], s[12:13], 0, v[0:1]
	s_mov_b32 m0, s18
	s_nop 0
	global_load_lds_dwordx4 v[144:145], off
	v_lshl_add_u64 v[144:145], s[12:13], 0, v[134:135]
	s_add_i32 m0, s18, 0x2000
	s_nop 0
	global_load_lds_dwordx4 v[144:145], off
	s_waitcnt vmcnt(6)
	s_barrier
	v_mfma_f32_16x16x32_bf16 v[46:49], v[234:237], v[172:175], v[46:49]
	v_mfma_f32_16x16x32_bf16 v[42:45], v[242:245], v[172:175], v[42:45]
	v_mfma_f32_16x16x32_bf16 v[30:33], v[234:237], v[180:183], v[30:33]
	v_mfma_f32_16x16x32_bf16 v[26:29], v[242:245], v[180:183], v[26:29]
	v_mfma_f32_16x16x32_bf16 v[14:17], v[234:237], v[188:191], v[14:17]
	v_mfma_f32_16x16x32_bf16 v[10:13], v[242:245], v[188:191], v[10:13]
	v_mfma_f32_16x16x32_bf16 v[6:9], v[234:237], v[196:199], v[6:9]
	v_mfma_f32_16x16x32_bf16 v[2:5], v[242:245], v[196:199], v[2:5]
	v_mfma_f32_16x16x32_bf16 v[46:49], v[238:241], v[176:179], v[46:49]
	v_mfma_f32_16x16x32_bf16 v[42:45], v[246:249], v[176:179], v[42:45]
	v_mfma_f32_16x16x32_bf16 v[30:33], v[238:241], v[184:187], v[30:33]
	v_mfma_f32_16x16x32_bf16 v[26:29], v[246:249], v[184:187], v[26:29]
	v_mfma_f32_16x16x32_bf16 v[14:17], v[238:241], v[192:195], v[14:17]
	v_mfma_f32_16x16x32_bf16 v[10:13], v[246:249], v[192:195], v[10:13]
	v_mfma_f32_16x16x32_bf16 v[6:9], v[238:241], v[200:203], v[6:9]
	v_mfma_f32_16x16x32_bf16 v[2:5], v[246:249], v[200:203], v[2:5]
	s_add_i32 s44, s44, 2
	s_add_u32 s42, s42, 0x100
	s_addc_u32 s43, s43, 0
	s_cmp_gt_u32 s44, 41
	s_mov_b64 s[12:13], s[14:15]
	s_barrier
	s_cbranch_scc0 .LBB0_115
	v_lshl_add_u32 v144, s46, 8, v140
	v_lshl_or_b32 v146, s49, 8, v142
	v_ashrrev_i32_e32 v147, 31, v146
	v_ashrrev_i32_e32 v145, 31, v144
	v_lshl_add_u64 v[146:147], v[146:147], 1, s[2:3]
	v_lshlrev_b64 v[148:149], 11, v[144:145]
	v_lshl_add_u64 v[148:149], v[146:147], 0, v[148:149]
	s_mov_b64 s[12:13], 0x40000
	v_cvt_pk_bf16_f32 v62, v62, v63
	v_cvt_pk_bf16_f32 v63, v64, v65
	v_cvt_pk_bf16_f32 v64, v58, v59
	v_add_co_u32_e32 v58, vcc, s79, v148
	v_cvt_pk_bf16_f32 v70, v70, v71
	v_cvt_pk_bf16_f32 v71, v72, v73
	v_cvt_pk_bf16_f32 v72, v66, v67
	v_lshl_add_u64 v[66:67], v[148:149], 0, s[12:13]
	v_addc_co_u32_e32 v59, vcc, 0, v149, vcc
	v_cvt_pk_bf16_f32 v46, v46, v47
	v_cvt_pk_bf16_f32 v47, v48, v49
	v_cvt_pk_bf16_f32 v48, v42, v43
	v_cvt_pk_bf16_f32 v49, v44, v45
	global_store_dwordx4 v[66:67], v[46:49], off offset:256
	s_mov_b64 s[12:13], 0x48000
	v_cvt_pk_bf16_f32 v110, v110, v111
	v_add_co_u32_e32 v48, vcc, s91, v148
	v_cvt_pk_bf16_f32 v111, v112, v113
	v_cvt_pk_bf16_f32 v112, v106, v107
	v_or_b32_e32 v106, 16, v144
	v_lshl_add_u64 v[46:47], v[148:149], 0, s[12:13]
	v_addc_co_u32_e32 v49, vcc, 0, v149, vcc
	v_cvt_pk_bf16_f32 v30, v30, v31
	v_cvt_pk_bf16_f32 v31, v32, v33
	v_cvt_pk_bf16_f32 v32, v26, v27
	v_cvt_pk_bf16_f32 v33, v28, v29
	v_ashrrev_i32_e32 v107, 31, v106
	v_cvt_pk_bf16_f32 v94, v94, v95
	v_cvt_pk_bf16_f32 v95, v96, v97
	v_cvt_pk_bf16_f32 v96, v90, v91
	v_or_b32_e32 v90, 32, v144
	global_store_dwordx4 v[46:47], v[30:33], off offset:256
	s_mov_b64 s[12:13], 0x50000
	v_cvt_pk_bf16_f32 v113, v108, v109
	v_add_co_u32_e32 v32, vcc, s92, v148
	v_lshlrev_b64 v[106:107], 11, v[106:107]
	v_ashrrev_i32_e32 v91, 31, v90
	v_cvt_pk_bf16_f32 v78, v78, v79
	v_cvt_pk_bf16_f32 v79, v80, v81
	v_cvt_pk_bf16_f32 v80, v74, v75
	v_or_b32_e32 v74, 48, v144
	v_lshl_add_u64 v[30:31], v[148:149], 0, s[12:13]
	v_addc_co_u32_e32 v33, vcc, 0, v149, vcc
	v_cvt_pk_bf16_f32 v14, v14, v15
	v_cvt_pk_bf16_f32 v15, v16, v17
	v_cvt_pk_bf16_f32 v16, v10, v11
	v_cvt_pk_bf16_f32 v17, v12, v13
	global_store_dwordx4 v[148:149], v[110:113], off offset:256
	v_cvt_pk_bf16_f32 v97, v92, v93
	v_lshlrev_b64 v[90:91], 11, v[90:91]
	v_lshl_add_u64 v[110:111], v[146:147], 0, v[106:107]
	v_ashrrev_i32_e32 v75, 31, v74
	global_store_dwordx4 v[30:31], v[14:17], off offset:256
	global_store_dwordx4 v[110:111], v[94:97], off offset:256
	v_cvt_pk_bf16_f32 v81, v76, v77
	v_add_co_u32_e32 v16, vcc, 0x58000, v148
	v_lshl_add_u64 v[94:95], v[146:147], 0, v[90:91]
	v_lshlrev_b64 v[74:75], 11, v[74:75]
	s_mov_b64 s[12:13], 0x58000
	v_addc_co_u32_e32 v17, vcc, 0, v149, vcc
	v_cvt_pk_bf16_f32 v126, v126, v127
	v_cvt_pk_bf16_f32 v127, v128, v129
	v_cvt_pk_bf16_f32 v128, v122, v123
	v_cvt_pk_bf16_f32 v129, v124, v125
	v_cvt_pk_bf16_f32 v106, v118, v119
	v_cvt_pk_bf16_f32 v107, v120, v121
	v_cvt_pk_bf16_f32 v108, v114, v115
	v_cvt_pk_bf16_f32 v109, v116, v117
	v_cvt_pk_bf16_f32 v90, v102, v103
	v_cvt_pk_bf16_f32 v91, v104, v105
	v_cvt_pk_bf16_f32 v92, v98, v99
	v_cvt_pk_bf16_f32 v93, v100, v101
	global_store_dwordx4 v[94:95], v[78:81], off offset:256
	v_cvt_pk_bf16_f32 v76, v82, v83
	v_cvt_pk_bf16_f32 v77, v84, v85
	v_lshl_add_u64 v[78:79], v[146:147], 0, v[74:75]
	v_cvt_pk_bf16_f32 v74, v86, v87
	v_cvt_pk_bf16_f32 v75, v88, v89
	v_cvt_pk_bf16_f32 v73, v68, v69
	v_cvt_pk_bf16_f32 v65, v60, v61
	v_cvt_pk_bf16_f32 v42, v54, v55
	v_cvt_pk_bf16_f32 v43, v56, v57
	v_cvt_pk_bf16_f32 v44, v50, v51
	v_cvt_pk_bf16_f32 v45, v52, v53
	v_cvt_pk_bf16_f32 v26, v38, v39
	v_cvt_pk_bf16_f32 v27, v40, v41
	v_cvt_pk_bf16_f32 v28, v34, v35
	v_cvt_pk_bf16_f32 v29, v36, v37
	v_lshl_add_u64 v[14:15], v[148:149], 0, s[12:13]
	v_cvt_pk_bf16_f32 v10, v22, v23
	v_cvt_pk_bf16_f32 v11, v24, v25
	v_cvt_pk_bf16_f32 v12, v18, v19
	v_cvt_pk_bf16_f32 v13, v20, v21
	v_cvt_pk_bf16_f32 v6, v6, v7
	v_cvt_pk_bf16_f32 v7, v8, v9
	v_cvt_pk_bf16_f32 v8, v2, v3
	v_cvt_pk_bf16_f32 v9, v4, v5
	s_and_b64 vcc, exec, s[40:41]
	s_mov_b32 s49, s50
	s_mov_b32 s46, s51
	s_mov_b64 s[14:15], s[10:11]
	s_mov_b64 s[12:13], s[8:9]
	global_store_dwordx4 v[148:149], v[126:129], off
	global_store_dwordx4 v[110:111], v[106:109], off
	global_store_dwordx4 v[94:95], v[90:93], off
	global_store_dwordx4 v[78:79], v[74:77], off
	global_store_dwordx4 v[78:79], v[70:73], off offset:256
	global_store_dwordx4 v[58:59], v[62:65], off
	global_store_dwordx4 v[48:49], v[42:45], off
	global_store_dwordx4 v[32:33], v[26:29], off
	global_store_dwordx4 v[16:17], v[10:13], off
	global_store_dwordx4 v[14:15], v[6:9], off offset:256
	s_cbranch_vccz .LBB0_104
	s_waitcnt vmcnt(0)
	s_cmpk_gt_u32 s1, 0xff
	s_cbranch_scc1 .LBB0_119
	s_barrier

.LBB0_202:
	s_add_u32 s38, s34, 0xfffc0080
	s_addc_u32 s39, s35, -1
	s_add_i32 s60, 0, 0x10000
	v_add_u32_e32 v148, s60, v141
	ds_read_b128 v[144:147], v148
	ds_read_b128 v[160:163], v148 offset:1024
	ds_read_b128 v[164:167], v148 offset:2048
	ds_read_b128 v[168:171], v148 offset:3072
	s_cmp_eq_u32 s59, 12
	s_cselect_b32 s39, s27, s39
	s_cselect_b32 s38, s55, s38
	s_cselect_b32 s45, s25, s58
	s_cselect_b32 s44, s56, s57
	v_lshl_add_u64 v[148:149], s[34:35], 0, v[138:139]
	s_add_i32 m0, s19, 0xc000
	ds_read_b128 v[172:175], v143
	ds_read_b128 v[176:179], v143 offset:1024
	ds_read_b128 v[180:183], v143 offset:2048
	ds_read_b128 v[184:187], v143 offset:3072
	ds_read_b128 v[188:191], v143 offset:4096
	ds_read_b128 v[192:195], v143 offset:5120
	ds_read_b128 v[196:199], v143 offset:6144
	ds_read_b128 v[200:203], v143 offset:7168
	global_load_lds_dwordx4 v[148:149], off
	v_lshl_add_u64 v[148:149], s[34:35], 0, v[136:137]
	s_add_i32 m0, s19, 0xe000
	s_nop 0
	global_load_lds_dwordx4 v[148:149], off
	s_waitcnt lgkmcnt(8)
	s_barrier
	s_waitcnt lgkmcnt(0)
	s_waitcnt lgkmcnt(0)
	v_mfma_f32_16x16x32_bf16 v[126:129], v[144:147], v[172:175], v[126:129]
	v_mfma_f32_16x16x32_bf16 v[122:125], v[164:167], v[172:175], v[122:125]
	v_mfma_f32_16x16x32_bf16 v[118:121], v[144:147], v[180:183], v[118:121]
	v_mfma_f32_16x16x32_bf16 v[114:117], v[164:167], v[180:183], v[114:117]
	v_mfma_f32_16x16x32_bf16 v[102:105], v[144:147], v[188:191], v[102:105]
	v_mfma_f32_16x16x32_bf16 v[98:101], v[164:167], v[188:191], v[98:101]
	v_mfma_f32_16x16x32_bf16 v[86:89], v[144:147], v[196:199], v[86:89]
	v_mfma_f32_16x16x32_bf16 v[82:85], v[164:167], v[196:199], v[82:85]
	v_mfma_f32_16x16x32_bf16 v[126:129], v[160:163], v[176:179], v[126:129]
	v_mfma_f32_16x16x32_bf16 v[122:125], v[168:171], v[176:179], v[122:125]
	v_mfma_f32_16x16x32_bf16 v[118:121], v[160:163], v[184:187], v[118:121]
	v_mfma_f32_16x16x32_bf16 v[114:117], v[168:171], v[184:187], v[114:117]
	v_mfma_f32_16x16x32_bf16 v[102:105], v[160:163], v[192:195], v[102:105]
	v_mfma_f32_16x16x32_bf16 v[98:101], v[168:171], v[192:195], v[98:101]
	v_mfma_f32_16x16x32_bf16 v[86:89], v[160:163], v[200:203], v[86:89]
	v_mfma_f32_16x16x32_bf16 v[82:85], v[168:171], v[200:203], v[82:85]
	s_barrier
	s_add_i32 s62, 0, 0x14000
	v_add_u32_e32 v148, s62, v141
	s_add_i32 s60, s60, s48
	ds_read_b128 v[234:237], v148
	ds_read_b128 v[238:241], v148 offset:1024
	ds_read_b128 v[242:245], v148 offset:2048
	ds_read_b128 v[246:249], v148 offset:3072
	v_lshl_add_u64 v[148:149], s[44:45], 0, v[0:1]
	s_mov_b32 m0, s60
	v_lshl_add_u64 v[204:205], s[44:45], 0, v[134:135]
	global_load_lds_dwordx4 v[148:149], off
	s_add_i32 m0, s60, 0x2000
	s_nop 0
	global_load_lds_dwordx4 v[204:205], off
	s_barrier
	s_waitcnt lgkmcnt(0)
	s_waitcnt lgkmcnt(0)
	v_mfma_f32_16x16x32_bf16 v[110:113], v[234:237], v[172:175], v[110:113]
	v_mfma_f32_16x16x32_bf16 v[106:109], v[242:245], v[172:175], v[106:109]
	v_mfma_f32_16x16x32_bf16 v[94:97], v[234:237], v[180:183], v[94:97]
	v_mfma_f32_16x16x32_bf16 v[90:93], v[242:245], v[180:183], v[90:93]
	v_mfma_f32_16x16x32_bf16 v[78:81], v[234:237], v[188:191], v[78:81]
	v_mfma_f32_16x16x32_bf16 v[74:77], v[242:245], v[188:191], v[74:77]
	v_mfma_f32_16x16x32_bf16 v[70:73], v[234:237], v[196:199], v[70:73]
	v_mfma_f32_16x16x32_bf16 v[66:69], v[242:245], v[196:199], v[66:69]
	v_mfma_f32_16x16x32_bf16 v[110:113], v[238:241], v[176:179], v[110:113]
	v_mfma_f32_16x16x32_bf16 v[106:109], v[246:249], v[176:179], v[106:109]
	v_mfma_f32_16x16x32_bf16 v[94:97], v[238:241], v[184:187], v[94:97]
	v_mfma_f32_16x16x32_bf16 v[90:93], v[246:249], v[184:187], v[90:93]
	v_mfma_f32_16x16x32_bf16 v[78:81], v[238:241], v[192:195], v[78:81]
	v_mfma_f32_16x16x32_bf16 v[74:77], v[246:249], v[192:195], v[74:77]
	v_mfma_f32_16x16x32_bf16 v[70:73], v[238:241], v[200:203], v[70:73]
	v_mfma_f32_16x16x32_bf16 v[66:69], v[246:249], v[200:203], v[66:69]
	s_mov_b32 m0, s19
	v_lshl_add_u64 v[250:251], s[38:39], 0, v[130:131]
	s_barrier
	ds_read_b128 v[172:175], v143 offset:16384
	ds_read_b128 v[176:179], v143 offset:17408
	ds_read_b128 v[180:183], v143 offset:18432
	ds_read_b128 v[184:187], v143 offset:19456
	ds_read_b128 v[188:191], v143 offset:20480
	ds_read_b128 v[192:195], v143 offset:21504
	ds_read_b128 v[196:199], v143 offset:22528
	ds_read_b128 v[200:203], v143 offset:23552
	global_load_lds_dwordx4 v[250:251], off
	v_lshl_add_u64 v[252:253], s[38:39], 0, v[132:133]
	s_mov_b32 m0, s49
	s_nop 0
	global_load_lds_dwordx4 v[252:253], off
	s_barrier
	s_waitcnt lgkmcnt(0)
	s_waitcnt lgkmcnt(0)
	v_mfma_f32_16x16x32_bf16 v[62:65], v[144:147], v[172:175], v[62:65]
	v_mfma_f32_16x16x32_bf16 v[58:61], v[164:167], v[172:175], v[58:61]
	v_mfma_f32_16x16x32_bf16 v[54:57], v[144:147], v[180:183], v[54:57]
	v_mfma_f32_16x16x32_bf16 v[50:53], v[164:167], v[180:183], v[50:53]
	v_mfma_f32_16x16x32_bf16 v[38:41], v[144:147], v[188:191], v[38:41]
	v_mfma_f32_16x16x32_bf16 v[34:37], v[164:167], v[188:191], v[34:37]
	v_mfma_f32_16x16x32_bf16 v[22:25], v[144:147], v[196:199], v[22:25]
	v_mfma_f32_16x16x32_bf16 v[18:21], v[164:167], v[196:199], v[18:21]
	v_mfma_f32_16x16x32_bf16 v[62:65], v[160:163], v[176:179], v[62:65]
	v_mfma_f32_16x16x32_bf16 v[58:61], v[168:171], v[176:179], v[58:61]
	v_mfma_f32_16x16x32_bf16 v[54:57], v[160:163], v[184:187], v[54:57]
	v_mfma_f32_16x16x32_bf16 v[50:53], v[168:171], v[184:187], v[50:53]
	v_mfma_f32_16x16x32_bf16 v[38:41], v[160:163], v[192:195], v[38:41]
	v_mfma_f32_16x16x32_bf16 v[34:37], v[168:171], v[192:195], v[34:37]
	v_mfma_f32_16x16x32_bf16 v[22:25], v[160:163], v[200:203], v[22:25]
	v_mfma_f32_16x16x32_bf16 v[18:21], v[168:171], v[200:203], v[18:21]
	s_barrier
	s_add_u32 s60, s44, 0x40000
	s_addc_u32 s61, s45, 0
	s_add_i32 s62, s62, s48
	v_lshl_add_u64 v[144:145], s[60:61], 0, v[0:1]
	s_mov_b32 m0, s62
	s_nop 0
	global_load_lds_dwordx4 v[144:145], off
	v_lshl_add_u64 v[144:145], s[60:61], 0, v[134:135]
	s_add_i32 m0, s62, 0x2000
	s_nop 0
	global_load_lds_dwordx4 v[144:145], off
	s_waitcnt vmcnt(6)
	s_barrier
	v_mfma_f32_16x16x32_bf16 v[46:49], v[234:237], v[172:175], v[46:49]
	v_mfma_f32_16x16x32_bf16 v[42:45], v[242:245], v[172:175], v[42:45]
	v_mfma_f32_16x16x32_bf16 v[30:33], v[234:237], v[180:183], v[30:33]
	v_mfma_f32_16x16x32_bf16 v[26:29], v[242:245], v[180:183], v[26:29]
	v_mfma_f32_16x16x32_bf16 v[14:17], v[234:237], v[188:191], v[14:17]
	v_mfma_f32_16x16x32_bf16 v[10:13], v[242:245], v[188:191], v[10:13]
	v_mfma_f32_16x16x32_bf16 v[6:9], v[234:237], v[196:199], v[6:9]
	v_mfma_f32_16x16x32_bf16 v[2:5], v[242:245], v[196:199], v[2:5]
	v_mfma_f32_16x16x32_bf16 v[46:49], v[238:241], v[176:179], v[46:49]
	v_mfma_f32_16x16x32_bf16 v[42:45], v[246:249], v[176:179], v[42:45]
	v_mfma_f32_16x16x32_bf16 v[30:33], v[238:241], v[184:187], v[30:33]
	v_mfma_f32_16x16x32_bf16 v[26:29], v[246:249], v[184:187], v[26:29]
	v_mfma_f32_16x16x32_bf16 v[14:17], v[238:241], v[192:195], v[14:17]
	v_mfma_f32_16x16x32_bf16 v[10:13], v[246:249], v[192:195], v[10:13]
	v_mfma_f32_16x16x32_bf16 v[6:9], v[238:241], v[200:203], v[6:9]
	v_mfma_f32_16x16x32_bf16 v[2:5], v[246:249], v[200:203], v[2:5]
	s_add_i32 s60, 0, 0x18000
	v_add_u32_e32 v159, s60, v141
	s_barrier
	ds_read_b128 v[144:147], v159
	ds_read_b128 v[160:163], v159 offset:1024
	ds_read_b128 v[164:167], v159 offset:2048
	ds_read_b128 v[168:171], v159 offset:3072
	s_add_u32 s38, s38, 0x40000
	s_addc_u32 s39, s39, 0
	s_mov_b32 m0, s50
	v_lshl_add_u64 v[234:235], s[38:39], 0, v[130:131]
	ds_read_b128 v[172:175], v143 offset:32768
	ds_read_b128 v[176:179], v143 offset:33792
	ds_read_b128 v[180:183], v143 offset:34816
	ds_read_b128 v[184:187], v143 offset:35840
	ds_read_b128 v[188:191], v143 offset:36864
	ds_read_b128 v[192:195], v143 offset:37888
	ds_read_b128 v[196:199], v143 offset:38912
	ds_read_b128 v[200:203], v143 offset:39936
	global_load_lds_dwordx4 v[234:235], off
	v_lshl_add_u64 v[234:235], s[38:39], 0, v[132:133]
	s_mov_b32 m0, s51
	s_nop 0
	global_load_lds_dwordx4 v[234:235], off
	s_waitcnt lgkmcnt(8)
	s_barrier
	s_waitcnt lgkmcnt(0)
	s_waitcnt lgkmcnt(0)
	v_mfma_f32_16x16x32_bf16 v[126:129], v[144:147], v[172:175], v[126:129]
	v_mfma_f32_16x16x32_bf16 v[122:125], v[164:167], v[172:175], v[122:125]
	v_mfma_f32_16x16x32_bf16 v[118:121], v[144:147], v[180:183], v[118:121]
	v_mfma_f32_16x16x32_bf16 v[114:117], v[164:167], v[180:183], v[114:117]
	v_mfma_f32_16x16x32_bf16 v[102:105], v[144:147], v[188:191], v[102:105]
	v_mfma_f32_16x16x32_bf16 v[98:101], v[164:167], v[188:191], v[98:101]
	v_mfma_f32_16x16x32_bf16 v[86:89], v[144:147], v[196:199], v[86:89]
	v_mfma_f32_16x16x32_bf16 v[82:85], v[164:167], v[196:199], v[82:85]
	v_mfma_f32_16x16x32_bf16 v[126:129], v[160:163], v[176:179], v[126:129]
	v_mfma_f32_16x16x32_bf16 v[122:125], v[168:171], v[176:179], v[122:125]
	v_mfma_f32_16x16x32_bf16 v[118:121], v[160:163], v[184:187], v[118:121]
	v_mfma_f32_16x16x32_bf16 v[114:117], v[168:171], v[184:187], v[114:117]
	v_mfma_f32_16x16x32_bf16 v[102:105], v[160:163], v[192:195], v[102:105]
	v_mfma_f32_16x16x32_bf16 v[98:101], v[168:171], v[192:195], v[98:101]
	v_mfma_f32_16x16x32_bf16 v[86:89], v[160:163], v[200:203], v[86:89]
	v_mfma_f32_16x16x32_bf16 v[82:85], v[168:171], v[200:203], v[82:85]
	s_barrier
	s_add_i32 s61, 0, 0x1c000
	s_add_i32 s38, s60, s48
	v_add_u32_e32 v159, s61, v141
	v_lshl_add_u64 v[148:149], v[148:149], 0, s[20:21]
	s_mov_b32 m0, s38
	ds_read_b128 v[234:237], v159
	ds_read_b128 v[238:241], v159 offset:1024
	ds_read_b128 v[242:245], v159 offset:2048
	ds_read_b128 v[246:249], v159 offset:3072
	global_load_lds_dwordx4 v[148:149], off
	v_lshl_add_u64 v[148:149], v[204:205], 0, s[20:21]
	s_add_i32 m0, s38, 0x2000
	s_nop 0
	global_load_lds_dwordx4 v[148:149], off
	s_barrier
	s_waitcnt lgkmcnt(0)
	s_waitcnt lgkmcnt(0)
	v_mfma_f32_16x16x32_bf16 v[110:113], v[234:237], v[172:175], v[110:113]
	v_mfma_f32_16x16x32_bf16 v[106:109], v[242:245], v[172:175], v[106:109]
	v_mfma_f32_16x16x32_bf16 v[94:97], v[234:237], v[180:183], v[94:97]
	v_mfma_f32_16x16x32_bf16 v[90:93], v[242:245], v[180:183], v[90:93]
	v_mfma_f32_16x16x32_bf16 v[78:81], v[234:237], v[188:191], v[78:81]
	v_mfma_f32_16x16x32_bf16 v[74:77], v[242:245], v[188:191], v[74:77]
	v_mfma_f32_16x16x32_bf16 v[70:73], v[234:237], v[196:199], v[70:73]
	v_mfma_f32_16x16x32_bf16 v[66:69], v[242:245], v[196:199], v[66:69]
	v_mfma_f32_16x16x32_bf16 v[110:113], v[238:241], v[176:179], v[110:113]
	v_mfma_f32_16x16x32_bf16 v[106:109], v[246:249], v[176:179], v[106:109]
	v_mfma_f32_16x16x32_bf16 v[94:97], v[238:241], v[184:187], v[94:97]
	v_mfma_f32_16x16x32_bf16 v[90:93], v[246:249], v[184:187], v[90:93]
	v_mfma_f32_16x16x32_bf16 v[78:81], v[238:241], v[192:195], v[78:81]
	v_mfma_f32_16x16x32_bf16 v[74:77], v[246:249], v[192:195], v[74:77]
	v_mfma_f32_16x16x32_bf16 v[70:73], v[238:241], v[200:203], v[70:73]
	v_mfma_f32_16x16x32_bf16 v[66:69], v[246:249], v[200:203], v[66:69]
	s_mov_b32 m0, s52
	v_lshl_add_u64 v[148:149], v[250:251], 0, s[20:21]
	s_barrier
	ds_read_b128 v[172:175], v143 offset:49152
	ds_read_b128 v[176:179], v143 offset:50176
	ds_read_b128 v[180:183], v143 offset:51200
	ds_read_b128 v[184:187], v143 offset:52224
	ds_read_b128 v[188:191], v143 offset:53248
	ds_read_b128 v[192:195], v143 offset:54272
	ds_read_b128 v[196:199], v143 offset:55296
	ds_read_b128 v[200:203], v143 offset:56320
	global_load_lds_dwordx4 v[148:149], off
	v_lshl_add_u64 v[148:149], v[252:253], 0, s[20:21]
	s_mov_b32 m0, s53
	s_nop 0
	global_load_lds_dwordx4 v[148:149], off
	s_barrier
	s_waitcnt lgkmcnt(0)
	s_waitcnt lgkmcnt(0)
	v_mfma_f32_16x16x32_bf16 v[62:65], v[144:147], v[172:175], v[62:65]
	v_mfma_f32_16x16x32_bf16 v[58:61], v[164:167], v[172:175], v[58:61]
	v_mfma_f32_16x16x32_bf16 v[54:57], v[144:147], v[180:183], v[54:57]
	v_mfma_f32_16x16x32_bf16 v[50:53], v[164:167], v[180:183], v[50:53]
	v_mfma_f32_16x16x32_bf16 v[38:41], v[144:147], v[188:191], v[38:41]
	v_mfma_f32_16x16x32_bf16 v[34:37], v[164:167], v[188:191], v[34:37]
	v_mfma_f32_16x16x32_bf16 v[22:25], v[144:147], v[196:199], v[22:25]
	v_mfma_f32_16x16x32_bf16 v[18:21], v[164:167], v[196:199], v[18:21]
	v_mfma_f32_16x16x32_bf16 v[62:65], v[160:163], v[176:179], v[62:65]
	v_mfma_f32_16x16x32_bf16 v[58:61], v[168:171], v[176:179], v[58:61]
	v_mfma_f32_16x16x32_bf16 v[54:57], v[160:163], v[184:187], v[54:57]
	v_mfma_f32_16x16x32_bf16 v[50:53], v[168:171], v[184:187], v[50:53]
	v_mfma_f32_16x16x32_bf16 v[38:41], v[160:163], v[192:195], v[38:41]
	v_mfma_f32_16x16x32_bf16 v[34:37], v[168:171], v[192:195], v[34:37]
	v_mfma_f32_16x16x32_bf16 v[22:25], v[160:163], v[200:203], v[22:25]
	v_mfma_f32_16x16x32_bf16 v[18:21], v[168:171], v[200:203], v[18:21]
	s_barrier
	s_add_u32 s38, s44, 0x40080
	s_addc_u32 s39, s45, 0
	s_add_i32 s44, s61, s48
	v_lshl_add_u64 v[144:145], s[38:39], 0, v[0:1]
	s_mov_b32 m0, s44
	s_nop 0
	global_load_lds_dwordx4 v[144:145], off
	v_lshl_add_u64 v[144:145], s[38:39], 0, v[134:135]
	s_add_i32 m0, s44, 0x2000
	s_nop 0
	global_load_lds_dwordx4 v[144:145], off
	s_waitcnt vmcnt(6)
	s_barrier
	v_mfma_f32_16x16x32_bf16 v[46:49], v[234:237], v[172:175], v[46:49]
	v_mfma_f32_16x16x32_bf16 v[42:45], v[242:245], v[172:175], v[42:45]
	v_mfma_f32_16x16x32_bf16 v[30:33], v[234:237], v[180:183], v[30:33]
	v_mfma_f32_16x16x32_bf16 v[26:29], v[242:245], v[180:183], v[26:29]
	v_mfma_f32_16x16x32_bf16 v[14:17], v[234:237], v[188:191], v[14:17]
	v_mfma_f32_16x16x32_bf16 v[10:13], v[242:245], v[188:191], v[10:13]
	v_mfma_f32_16x16x32_bf16 v[6:9], v[234:237], v[196:199], v[6:9]
	v_mfma_f32_16x16x32_bf16 v[2:5], v[242:245], v[196:199], v[2:5]
	v_mfma_f32_16x16x32_bf16 v[46:49], v[238:241], v[176:179], v[46:49]
	v_mfma_f32_16x16x32_bf16 v[42:45], v[246:249], v[176:179], v[42:45]
	v_mfma_f32_16x16x32_bf16 v[30:33], v[238:241], v[184:187], v[30:33]
	v_mfma_f32_16x16x32_bf16 v[26:29], v[246:249], v[184:187], v[26:29]
	v_mfma_f32_16x16x32_bf16 v[14:17], v[238:241], v[192:195], v[14:17]
	v_mfma_f32_16x16x32_bf16 v[10:13], v[246:249], v[192:195], v[10:13]
	v_mfma_f32_16x16x32_bf16 v[6:9], v[238:241], v[200:203], v[6:9]
	v_mfma_f32_16x16x32_bf16 v[2:5], v[246:249], v[200:203], v[2:5]
	s_add_i32 s59, s59, 2
	s_add_u32 s57, s57, 0x100
	s_addc_u32 s58, s58, 0
	s_add_u32 s34, s34, 0x100
	s_addc_u32 s35, s35, 0
	s_cmp_gt_u32 s59, 13
	s_barrier
	s_cbranch_scc0 .LBB0_202
	v_lshl_add_u32 v144, s18, 8, v140
	v_lshl_or_b32 v146, s54, 8, v142
	v_ashrrev_i32_e32 v147, 31, v146
	v_ashrrev_i32_e32 v145, 31, v144
	v_lshl_add_u64 v[146:147], v[146:147], 1, s[14:15]
	v_lshlrev_b64 v[148:149], 11, v[144:145]
	v_lshl_add_u64 v[148:149], v[146:147], 0, v[148:149]
	s_mov_b64 s[34:35], 0x40000
	v_cvt_pk_bf16_f32 v62, v62, v63
	v_cvt_pk_bf16_f32 v63, v64, v65
	v_cvt_pk_bf16_f32 v64, v58, v59
	v_add_co_u32_e32 v58, vcc, s79, v148
	v_cvt_pk_bf16_f32 v70, v70, v71
	v_cvt_pk_bf16_f32 v71, v72, v73
	v_cvt_pk_bf16_f32 v72, v66, v67
	v_lshl_add_u64 v[66:67], v[148:149], 0, s[34:35]
	v_addc_co_u32_e32 v59, vcc, 0, v149, vcc
	v_cvt_pk_bf16_f32 v46, v46, v47
	v_cvt_pk_bf16_f32 v47, v48, v49
	v_cvt_pk_bf16_f32 v48, v42, v43
	v_cvt_pk_bf16_f32 v49, v44, v45
	global_store_dwordx4 v[66:67], v[46:49], off offset:256
	s_mov_b64 s[34:35], 0x48000
	v_cvt_pk_bf16_f32 v110, v110, v111
	v_add_co_u32_e32 v48, vcc, s91, v148
	v_cvt_pk_bf16_f32 v111, v112, v113
	v_cvt_pk_bf16_f32 v112, v106, v107
	v_or_b32_e32 v106, 16, v144
	v_lshl_add_u64 v[46:47], v[148:149], 0, s[34:35]
	v_addc_co_u32_e32 v49, vcc, 0, v149, vcc
	v_cvt_pk_bf16_f32 v30, v30, v31
	v_cvt_pk_bf16_f32 v31, v32, v33
	v_cvt_pk_bf16_f32 v32, v26, v27
	v_cvt_pk_bf16_f32 v33, v28, v29
	v_ashrrev_i32_e32 v107, 31, v106
	v_cvt_pk_bf16_f32 v94, v94, v95
	v_cvt_pk_bf16_f32 v95, v96, v97
	v_cvt_pk_bf16_f32 v96, v90, v91
	v_or_b32_e32 v90, 32, v144
	global_store_dwordx4 v[46:47], v[30:33], off offset:256
	s_mov_b64 s[34:35], 0x50000
	v_cvt_pk_bf16_f32 v113, v108, v109
	v_add_co_u32_e32 v32, vcc, s92, v148
	v_lshlrev_b64 v[106:107], 11, v[106:107]
	v_ashrrev_i32_e32 v91, 31, v90
	v_cvt_pk_bf16_f32 v78, v78, v79
	v_cvt_pk_bf16_f32 v79, v80, v81
	v_cvt_pk_bf16_f32 v80, v74, v75
	v_or_b32_e32 v74, 48, v144
	v_lshl_add_u64 v[30:31], v[148:149], 0, s[34:35]
	v_addc_co_u32_e32 v33, vcc, 0, v149, vcc
	v_cvt_pk_bf16_f32 v14, v14, v15
	v_cvt_pk_bf16_f32 v15, v16, v17
	v_cvt_pk_bf16_f32 v16, v10, v11
	v_cvt_pk_bf16_f32 v17, v12, v13
	global_store_dwordx4 v[148:149], v[110:113], off offset:256
	v_cvt_pk_bf16_f32 v97, v92, v93
	v_lshlrev_b64 v[90:91], 11, v[90:91]
	v_lshl_add_u64 v[110:111], v[146:147], 0, v[106:107]
	v_ashrrev_i32_e32 v75, 31, v74
	global_store_dwordx4 v[30:31], v[14:17], off offset:256
	global_store_dwordx4 v[110:111], v[94:97], off offset:256
	v_cvt_pk_bf16_f32 v81, v76, v77
	v_add_co_u32_e32 v16, vcc, 0x58000, v148
	v_lshl_add_u64 v[94:95], v[146:147], 0, v[90:91]
	v_lshlrev_b64 v[74:75], 11, v[74:75]
	s_mov_b64 s[34:35], 0x58000
	v_addc_co_u32_e32 v17, vcc, 0, v149, vcc
	v_cvt_pk_bf16_f32 v126, v126, v127
	v_cvt_pk_bf16_f32 v127, v128, v129
	v_cvt_pk_bf16_f32 v128, v122, v123
	v_cvt_pk_bf16_f32 v129, v124, v125
	v_cvt_pk_bf16_f32 v106, v118, v119
	v_cvt_pk_bf16_f32 v107, v120, v121
	v_cvt_pk_bf16_f32 v108, v114, v115
	v_cvt_pk_bf16_f32 v109, v116, v117
	v_cvt_pk_bf16_f32 v90, v102, v103
	v_cvt_pk_bf16_f32 v91, v104, v105
	v_cvt_pk_bf16_f32 v92, v98, v99
	v_cvt_pk_bf16_f32 v93, v100, v101
	global_store_dwordx4 v[94:95], v[78:81], off offset:256
	v_cvt_pk_bf16_f32 v76, v82, v83
	v_cvt_pk_bf16_f32 v77, v84, v85
	v_lshl_add_u64 v[78:79], v[146:147], 0, v[74:75]
	v_cvt_pk_bf16_f32 v74, v86, v87
	v_cvt_pk_bf16_f32 v75, v88, v89
	v_cvt_pk_bf16_f32 v73, v68, v69
	v_cvt_pk_bf16_f32 v65, v60, v61
	v_cvt_pk_bf16_f32 v42, v54, v55
	v_cvt_pk_bf16_f32 v43, v56, v57
	v_cvt_pk_bf16_f32 v44, v50, v51
	v_cvt_pk_bf16_f32 v45, v52, v53
	v_cvt_pk_bf16_f32 v26, v38, v39
	v_cvt_pk_bf16_f32 v27, v40, v41
	v_cvt_pk_bf16_f32 v28, v34, v35
	v_cvt_pk_bf16_f32 v29, v36, v37
	v_lshl_add_u64 v[14:15], v[148:149], 0, s[34:35]
	v_cvt_pk_bf16_f32 v10, v22, v23
	v_cvt_pk_bf16_f32 v11, v24, v25
	v_cvt_pk_bf16_f32 v12, v18, v19
	v_cvt_pk_bf16_f32 v13, v20, v21
	v_cvt_pk_bf16_f32 v6, v6, v7
	v_cvt_pk_bf16_f32 v7, v8, v9
	v_cvt_pk_bf16_f32 v8, v2, v3
	v_cvt_pk_bf16_f32 v9, v4, v5
	s_and_b64 vcc, exec, s[22:23]
	s_mov_b32 s54, s24
	s_mov_b32 s18, s26
	s_mov_b64 s[34:35], s[30:31]
	s_mov_b64 s[44:45], s[28:29]
	s_movk_i32 s59, 0x7f
	s_movk_i32 s58, 0x15ff
	s_mov_b32 s57, s67
	global_store_dwordx4 v[148:149], v[126:129], off
	global_store_dwordx4 v[110:111], v[106:109], off
	global_store_dwordx4 v[94:95], v[90:93], off
	global_store_dwordx4 v[78:79], v[74:77], off
	global_store_dwordx4 v[78:79], v[70:73], off offset:256
	global_store_dwordx4 v[58:59], v[62:65], off
	global_store_dwordx4 v[48:49], v[42:45], off
	global_store_dwordx4 v[32:33], v[26:29], off
	global_store_dwordx4 v[16:17], v[10:13], off
	global_store_dwordx4 v[14:15], v[6:9], off offset:256
	s_cbranch_vccz .LBB0_195
	s_waitcnt vmcnt(0)
	v_readlane_b32 s54, v255, 3
	s_mov_b32 s56, s66
	s_cmpk_gt_u32 s1, 0xff
	v_readlane_b32 s55, v255, 4
	s_cbranch_scc1 .LBB0_206
	s_barrier

.LBB0_253:
	s_add_u32 s22, s18, 0x100
	s_addc_u32 s23, s19, 0
	s_add_i32 s49, 0, 0x10000
	v_add_u32_e32 v148, s49, v141
	ds_read_b128 v[144:147], v148
	ds_read_b128 v[160:163], v148 offset:1024
	ds_read_b128 v[164:167], v148 offset:2048
	ds_read_b128 v[168:171], v148 offset:3072
	s_cmp_eq_u32 s48, 40
	s_cselect_b32 s27, s13, s23
	s_cselect_b32 s26, s12, s22
	s_cselect_b32 s25, s15, s41
	s_cselect_b32 s24, s14, s40
	v_lshl_add_u64 v[148:149], s[18:19], 0, v[138:139]
	s_add_i32 m0, s34, 0xc000
	ds_read_b128 v[172:175], v143
	ds_read_b128 v[176:179], v143 offset:1024
	ds_read_b128 v[180:183], v143 offset:2048
	ds_read_b128 v[184:187], v143 offset:3072
	ds_read_b128 v[188:191], v143 offset:4096
	ds_read_b128 v[192:195], v143 offset:5120
	ds_read_b128 v[196:199], v143 offset:6144
	ds_read_b128 v[200:203], v143 offset:7168
	global_load_lds_dwordx4 v[148:149], off
	v_lshl_add_u64 v[148:149], s[18:19], 0, v[136:137]
	s_add_i32 m0, s34, 0xe000
	s_nop 0
	global_load_lds_dwordx4 v[148:149], off
	s_waitcnt lgkmcnt(8)
	s_barrier
	s_waitcnt lgkmcnt(0)
	s_waitcnt lgkmcnt(0)
	v_mfma_f32_16x16x32_bf16 v[126:129], v[144:147], v[172:175], v[126:129]
	v_mfma_f32_16x16x32_bf16 v[122:125], v[164:167], v[172:175], v[122:125]
	v_mfma_f32_16x16x32_bf16 v[118:121], v[144:147], v[180:183], v[118:121]
	v_mfma_f32_16x16x32_bf16 v[114:117], v[164:167], v[180:183], v[114:117]
	v_mfma_f32_16x16x32_bf16 v[102:105], v[144:147], v[188:191], v[102:105]
	v_mfma_f32_16x16x32_bf16 v[98:101], v[164:167], v[188:191], v[98:101]
	v_mfma_f32_16x16x32_bf16 v[86:89], v[144:147], v[196:199], v[86:89]
	v_mfma_f32_16x16x32_bf16 v[82:85], v[164:167], v[196:199], v[82:85]
	v_mfma_f32_16x16x32_bf16 v[126:129], v[160:163], v[176:179], v[126:129]
	v_mfma_f32_16x16x32_bf16 v[122:125], v[168:171], v[176:179], v[122:125]
	v_mfma_f32_16x16x32_bf16 v[118:121], v[160:163], v[184:187], v[118:121]
	v_mfma_f32_16x16x32_bf16 v[114:117], v[168:171], v[184:187], v[114:117]
	v_mfma_f32_16x16x32_bf16 v[102:105], v[160:163], v[192:195], v[102:105]
	v_mfma_f32_16x16x32_bf16 v[98:101], v[168:171], v[192:195], v[98:101]
	v_mfma_f32_16x16x32_bf16 v[86:89], v[160:163], v[200:203], v[86:89]
	v_mfma_f32_16x16x32_bf16 v[82:85], v[168:171], v[200:203], v[82:85]
	s_barrier
	s_add_i32 s50, 0, 0x14000
	v_add_u32_e32 v148, s50, v141
	s_add_i32 s18, s49, s31
	ds_read_b128 v[234:237], v148
	ds_read_b128 v[238:241], v148 offset:1024
	ds_read_b128 v[242:245], v148 offset:2048
	ds_read_b128 v[246:249], v148 offset:3072
	v_lshl_add_u64 v[148:149], s[24:25], 0, v[0:1]
	s_mov_b32 m0, s18
	v_lshl_add_u64 v[204:205], s[24:25], 0, v[134:135]
	global_load_lds_dwordx4 v[148:149], off
	s_add_i32 m0, s18, 0x2000
	s_nop 0
	global_load_lds_dwordx4 v[204:205], off
	s_barrier
	s_waitcnt lgkmcnt(0)
	s_waitcnt lgkmcnt(0)
	v_mfma_f32_16x16x32_bf16 v[110:113], v[234:237], v[172:175], v[110:113]
	v_mfma_f32_16x16x32_bf16 v[106:109], v[242:245], v[172:175], v[106:109]
	v_mfma_f32_16x16x32_bf16 v[94:97], v[234:237], v[180:183], v[94:97]
	v_mfma_f32_16x16x32_bf16 v[90:93], v[242:245], v[180:183], v[90:93]
	v_mfma_f32_16x16x32_bf16 v[78:81], v[234:237], v[188:191], v[78:81]
	v_mfma_f32_16x16x32_bf16 v[74:77], v[242:245], v[188:191], v[74:77]
	v_mfma_f32_16x16x32_bf16 v[70:73], v[234:237], v[196:199], v[70:73]
	v_mfma_f32_16x16x32_bf16 v[66:69], v[242:245], v[196:199], v[66:69]
	v_mfma_f32_16x16x32_bf16 v[110:113], v[238:241], v[176:179], v[110:113]
	v_mfma_f32_16x16x32_bf16 v[106:109], v[246:249], v[176:179], v[106:109]
	v_mfma_f32_16x16x32_bf16 v[94:97], v[238:241], v[184:187], v[94:97]
	v_mfma_f32_16x16x32_bf16 v[90:93], v[246:249], v[184:187], v[90:93]
	v_mfma_f32_16x16x32_bf16 v[78:81], v[238:241], v[192:195], v[78:81]
	v_mfma_f32_16x16x32_bf16 v[74:77], v[246:249], v[192:195], v[74:77]
	v_mfma_f32_16x16x32_bf16 v[70:73], v[238:241], v[200:203], v[70:73]
	v_mfma_f32_16x16x32_bf16 v[66:69], v[246:249], v[200:203], v[66:69]
	s_mov_b32 m0, s34
	v_lshl_add_u64 v[250:251], s[26:27], 0, v[130:131]
	s_barrier
	ds_read_b128 v[172:175], v143 offset:16384
	ds_read_b128 v[176:179], v143 offset:17408
	ds_read_b128 v[180:183], v143 offset:18432
	ds_read_b128 v[184:187], v143 offset:19456
	ds_read_b128 v[188:191], v143 offset:20480
	ds_read_b128 v[192:195], v143 offset:21504
	ds_read_b128 v[196:199], v143 offset:22528
	ds_read_b128 v[200:203], v143 offset:23552
	global_load_lds_dwordx4 v[250:251], off
	v_lshl_add_u64 v[252:253], s[26:27], 0, v[132:133]
	s_mov_b32 m0, s35
	s_nop 0
	global_load_lds_dwordx4 v[252:253], off
	s_barrier
	s_waitcnt lgkmcnt(0)
	s_waitcnt lgkmcnt(0)
	v_mfma_f32_16x16x32_bf16 v[62:65], v[144:147], v[172:175], v[62:65]
	v_mfma_f32_16x16x32_bf16 v[58:61], v[164:167], v[172:175], v[58:61]
	v_mfma_f32_16x16x32_bf16 v[54:57], v[144:147], v[180:183], v[54:57]
	v_mfma_f32_16x16x32_bf16 v[50:53], v[164:167], v[180:183], v[50:53]
	v_mfma_f32_16x16x32_bf16 v[38:41], v[144:147], v[188:191], v[38:41]
	v_mfma_f32_16x16x32_bf16 v[34:37], v[164:167], v[188:191], v[34:37]
	v_mfma_f32_16x16x32_bf16 v[22:25], v[144:147], v[196:199], v[22:25]
	v_mfma_f32_16x16x32_bf16 v[18:21], v[164:167], v[196:199], v[18:21]
	v_mfma_f32_16x16x32_bf16 v[62:65], v[160:163], v[176:179], v[62:65]
	v_mfma_f32_16x16x32_bf16 v[58:61], v[168:171], v[176:179], v[58:61]
	v_mfma_f32_16x16x32_bf16 v[54:57], v[160:163], v[184:187], v[54:57]
	v_mfma_f32_16x16x32_bf16 v[50:53], v[168:171], v[184:187], v[50:53]
	v_mfma_f32_16x16x32_bf16 v[38:41], v[160:163], v[192:195], v[38:41]
	v_mfma_f32_16x16x32_bf16 v[34:37], v[168:171], v[192:195], v[34:37]
	v_mfma_f32_16x16x32_bf16 v[22:25], v[160:163], v[200:203], v[22:25]
	v_mfma_f32_16x16x32_bf16 v[18:21], v[168:171], v[200:203], v[18:21]
	s_barrier
	s_add_u32 s18, s24, 0xb0000
	s_addc_u32 s19, s25, 0
	s_add_i32 s49, s50, s31
	v_lshl_add_u64 v[144:145], s[18:19], 0, v[0:1]
	s_mov_b32 m0, s49
	s_nop 0
	global_load_lds_dwordx4 v[144:145], off
	v_lshl_add_u64 v[144:145], s[18:19], 0, v[134:135]
	s_add_i32 m0, s49, 0x2000
	s_nop 0
	global_load_lds_dwordx4 v[144:145], off
	s_waitcnt vmcnt(6)
	s_barrier
	v_mfma_f32_16x16x32_bf16 v[46:49], v[234:237], v[172:175], v[46:49]
	v_mfma_f32_16x16x32_bf16 v[42:45], v[242:245], v[172:175], v[42:45]
	v_mfma_f32_16x16x32_bf16 v[30:33], v[234:237], v[180:183], v[30:33]
	v_mfma_f32_16x16x32_bf16 v[26:29], v[242:245], v[180:183], v[26:29]
	v_mfma_f32_16x16x32_bf16 v[14:17], v[234:237], v[188:191], v[14:17]
	v_mfma_f32_16x16x32_bf16 v[10:13], v[242:245], v[188:191], v[10:13]
	v_mfma_f32_16x16x32_bf16 v[6:9], v[234:237], v[196:199], v[6:9]
	v_mfma_f32_16x16x32_bf16 v[2:5], v[242:245], v[196:199], v[2:5]
	v_mfma_f32_16x16x32_bf16 v[46:49], v[238:241], v[176:179], v[46:49]
	v_mfma_f32_16x16x32_bf16 v[42:45], v[246:249], v[176:179], v[42:45]
	v_mfma_f32_16x16x32_bf16 v[30:33], v[238:241], v[184:187], v[30:33]
	v_mfma_f32_16x16x32_bf16 v[26:29], v[246:249], v[184:187], v[26:29]
	v_mfma_f32_16x16x32_bf16 v[14:17], v[238:241], v[192:195], v[14:17]
	v_mfma_f32_16x16x32_bf16 v[10:13], v[246:249], v[192:195], v[10:13]
	v_mfma_f32_16x16x32_bf16 v[6:9], v[238:241], v[200:203], v[6:9]
	v_mfma_f32_16x16x32_bf16 v[2:5], v[246:249], v[200:203], v[2:5]
	s_add_i32 s49, 0, 0x18000
	v_add_u32_e32 v159, s49, v141
	s_barrier
	ds_read_b128 v[144:147], v159
	ds_read_b128 v[160:163], v159 offset:1024
	ds_read_b128 v[164:167], v159 offset:2048
	ds_read_b128 v[168:171], v159 offset:3072
	s_add_u32 s18, s26, 0xb0000
	s_addc_u32 s19, s27, 0
	s_mov_b32 m0, s38
	v_lshl_add_u64 v[234:235], s[18:19], 0, v[130:131]
	ds_read_b128 v[172:175], v143 offset:32768
	ds_read_b128 v[176:179], v143 offset:33792
	ds_read_b128 v[180:183], v143 offset:34816
	ds_read_b128 v[184:187], v143 offset:35840
	ds_read_b128 v[188:191], v143 offset:36864
	ds_read_b128 v[192:195], v143 offset:37888
	ds_read_b128 v[196:199], v143 offset:38912
	ds_read_b128 v[200:203], v143 offset:39936
	global_load_lds_dwordx4 v[234:235], off
	v_lshl_add_u64 v[234:235], s[18:19], 0, v[132:133]
	s_mov_b32 m0, s39
	s_nop 0
	global_load_lds_dwordx4 v[234:235], off
	s_waitcnt lgkmcnt(8)
	s_barrier
	s_waitcnt lgkmcnt(0)
	s_waitcnt lgkmcnt(0)
	v_mfma_f32_16x16x32_bf16 v[126:129], v[144:147], v[172:175], v[126:129]
	v_mfma_f32_16x16x32_bf16 v[122:125], v[164:167], v[172:175], v[122:125]
	v_mfma_f32_16x16x32_bf16 v[118:121], v[144:147], v[180:183], v[118:121]
	v_mfma_f32_16x16x32_bf16 v[114:117], v[164:167], v[180:183], v[114:117]
	v_mfma_f32_16x16x32_bf16 v[102:105], v[144:147], v[188:191], v[102:105]
	v_mfma_f32_16x16x32_bf16 v[98:101], v[164:167], v[188:191], v[98:101]
	v_mfma_f32_16x16x32_bf16 v[86:89], v[144:147], v[196:199], v[86:89]
	v_mfma_f32_16x16x32_bf16 v[82:85], v[164:167], v[196:199], v[82:85]
	v_mfma_f32_16x16x32_bf16 v[126:129], v[160:163], v[176:179], v[126:129]
	v_mfma_f32_16x16x32_bf16 v[122:125], v[168:171], v[176:179], v[122:125]
	v_mfma_f32_16x16x32_bf16 v[118:121], v[160:163], v[184:187], v[118:121]
	v_mfma_f32_16x16x32_bf16 v[114:117], v[168:171], v[184:187], v[114:117]
	v_mfma_f32_16x16x32_bf16 v[102:105], v[160:163], v[192:195], v[102:105]
	v_mfma_f32_16x16x32_bf16 v[98:101], v[168:171], v[192:195], v[98:101]
	v_mfma_f32_16x16x32_bf16 v[86:89], v[160:163], v[200:203], v[86:89]
	v_mfma_f32_16x16x32_bf16 v[82:85], v[168:171], v[200:203], v[82:85]
	s_barrier
	s_add_i32 s26, 0, 0x1c000
	s_add_i32 s18, s49, s31
	v_add_u32_e32 v159, s26, v141
	v_lshl_add_u64 v[148:149], v[148:149], 0, s[20:21]
	s_mov_b32 m0, s18
	ds_read_b128 v[234:237], v159
	ds_read_b128 v[238:241], v159 offset:1024
	ds_read_b128 v[242:245], v159 offset:2048
	ds_read_b128 v[246:249], v159 offset:3072
	global_load_lds_dwordx4 v[148:149], off
	v_lshl_add_u64 v[148:149], v[204:205], 0, s[20:21]
	s_add_i32 m0, s18, 0x2000
	s_nop 0
	global_load_lds_dwordx4 v[148:149], off
	s_barrier
	s_waitcnt lgkmcnt(0)
	s_waitcnt lgkmcnt(0)
	v_mfma_f32_16x16x32_bf16 v[110:113], v[234:237], v[172:175], v[110:113]
	v_mfma_f32_16x16x32_bf16 v[106:109], v[242:245], v[172:175], v[106:109]
	v_mfma_f32_16x16x32_bf16 v[94:97], v[234:237], v[180:183], v[94:97]
	v_mfma_f32_16x16x32_bf16 v[90:93], v[242:245], v[180:183], v[90:93]
	v_mfma_f32_16x16x32_bf16 v[78:81], v[234:237], v[188:191], v[78:81]
	v_mfma_f32_16x16x32_bf16 v[74:77], v[242:245], v[188:191], v[74:77]
	v_mfma_f32_16x16x32_bf16 v[70:73], v[234:237], v[196:199], v[70:73]
	v_mfma_f32_16x16x32_bf16 v[66:69], v[242:245], v[196:199], v[66:69]
	v_mfma_f32_16x16x32_bf16 v[110:113], v[238:241], v[176:179], v[110:113]
	v_mfma_f32_16x16x32_bf16 v[106:109], v[246:249], v[176:179], v[106:109]
	v_mfma_f32_16x16x32_bf16 v[94:97], v[238:241], v[184:187], v[94:97]
	v_mfma_f32_16x16x32_bf16 v[90:93], v[246:249], v[184:187], v[90:93]
	v_mfma_f32_16x16x32_bf16 v[78:81], v[238:241], v[192:195], v[78:81]
	v_mfma_f32_16x16x32_bf16 v[74:77], v[246:249], v[192:195], v[74:77]
	v_mfma_f32_16x16x32_bf16 v[70:73], v[238:241], v[200:203], v[70:73]
	v_mfma_f32_16x16x32_bf16 v[66:69], v[246:249], v[200:203], v[66:69]
	s_mov_b32 m0, s42
	v_lshl_add_u64 v[148:149], v[250:251], 0, s[20:21]
	s_barrier
	ds_read_b128 v[172:175], v143 offset:49152
	ds_read_b128 v[176:179], v143 offset:50176
	ds_read_b128 v[180:183], v143 offset:51200
	ds_read_b128 v[184:187], v143 offset:52224
	ds_read_b128 v[188:191], v143 offset:53248
	ds_read_b128 v[192:195], v143 offset:54272
	ds_read_b128 v[196:199], v143 offset:55296
	ds_read_b128 v[200:203], v143 offset:56320
	global_load_lds_dwordx4 v[148:149], off
	v_lshl_add_u64 v[148:149], v[252:253], 0, s[20:21]
	s_mov_b32 m0, s43
	s_nop 0
	global_load_lds_dwordx4 v[148:149], off
	s_barrier
	s_waitcnt lgkmcnt(0)
	s_waitcnt lgkmcnt(0)
	v_mfma_f32_16x16x32_bf16 v[62:65], v[144:147], v[172:175], v[62:65]
	v_mfma_f32_16x16x32_bf16 v[58:61], v[164:167], v[172:175], v[58:61]
	v_mfma_f32_16x16x32_bf16 v[54:57], v[144:147], v[180:183], v[54:57]
	v_mfma_f32_16x16x32_bf16 v[50:53], v[164:167], v[180:183], v[50:53]
	v_mfma_f32_16x16x32_bf16 v[38:41], v[144:147], v[188:191], v[38:41]
	v_mfma_f32_16x16x32_bf16 v[34:37], v[164:167], v[188:191], v[34:37]
	v_mfma_f32_16x16x32_bf16 v[22:25], v[144:147], v[196:199], v[22:25]
	v_mfma_f32_16x16x32_bf16 v[18:21], v[164:167], v[196:199], v[18:21]
	v_mfma_f32_16x16x32_bf16 v[62:65], v[160:163], v[176:179], v[62:65]
	v_mfma_f32_16x16x32_bf16 v[58:61], v[168:171], v[176:179], v[58:61]
	v_mfma_f32_16x16x32_bf16 v[54:57], v[160:163], v[184:187], v[54:57]
	v_mfma_f32_16x16x32_bf16 v[50:53], v[168:171], v[184:187], v[50:53]
	v_mfma_f32_16x16x32_bf16 v[38:41], v[160:163], v[192:195], v[38:41]
	v_mfma_f32_16x16x32_bf16 v[34:37], v[168:171], v[192:195], v[34:37]
	v_mfma_f32_16x16x32_bf16 v[22:25], v[160:163], v[200:203], v[22:25]
	v_mfma_f32_16x16x32_bf16 v[18:21], v[168:171], v[200:203], v[18:21]
	s_barrier
	s_add_u32 s18, s24, 0xb0080
	s_addc_u32 s19, s25, 0
	s_add_i32 s24, s26, s31
	v_lshl_add_u64 v[144:145], s[18:19], 0, v[0:1]
	s_mov_b32 m0, s24
	s_nop 0
	global_load_lds_dwordx4 v[144:145], off
	v_lshl_add_u64 v[144:145], s[18:19], 0, v[134:135]
	s_add_i32 m0, s24, 0x2000
	s_nop 0
	global_load_lds_dwordx4 v[144:145], off
	s_waitcnt vmcnt(6)
	s_barrier
	v_mfma_f32_16x16x32_bf16 v[46:49], v[234:237], v[172:175], v[46:49]
	v_mfma_f32_16x16x32_bf16 v[42:45], v[242:245], v[172:175], v[42:45]
	v_mfma_f32_16x16x32_bf16 v[30:33], v[234:237], v[180:183], v[30:33]
	v_mfma_f32_16x16x32_bf16 v[26:29], v[242:245], v[180:183], v[26:29]
	v_mfma_f32_16x16x32_bf16 v[14:17], v[234:237], v[188:191], v[14:17]
	v_mfma_f32_16x16x32_bf16 v[10:13], v[242:245], v[188:191], v[10:13]
	v_mfma_f32_16x16x32_bf16 v[6:9], v[234:237], v[196:199], v[6:9]
	v_mfma_f32_16x16x32_bf16 v[2:5], v[242:245], v[196:199], v[2:5]
	v_mfma_f32_16x16x32_bf16 v[46:49], v[238:241], v[176:179], v[46:49]
	v_mfma_f32_16x16x32_bf16 v[42:45], v[246:249], v[176:179], v[42:45]
	v_mfma_f32_16x16x32_bf16 v[30:33], v[238:241], v[184:187], v[30:33]
	v_mfma_f32_16x16x32_bf16 v[26:29], v[246:249], v[184:187], v[26:29]
	v_mfma_f32_16x16x32_bf16 v[14:17], v[238:241], v[192:195], v[14:17]
	v_mfma_f32_16x16x32_bf16 v[10:13], v[246:249], v[192:195], v[10:13]
	v_mfma_f32_16x16x32_bf16 v[6:9], v[238:241], v[200:203], v[6:9]
	v_mfma_f32_16x16x32_bf16 v[2:5], v[246:249], v[200:203], v[2:5]
	s_add_i32 s48, s48, 2
	s_add_u32 s40, s40, 0x100
	s_addc_u32 s41, s41, 0
	s_cmp_gt_u32 s48, 41
	s_mov_b64 s[18:19], s[22:23]
	s_barrier
	s_cbranch_scc0 .LBB0_253
	v_lshl_add_u32 v144, s44, 8, v140
	v_lshl_or_b32 v146, s45, 8, v142
	v_ashrrev_i32_e32 v147, 31, v146
	v_ashrrev_i32_e32 v145, 31, v144
	v_lshl_add_u64 v[146:147], v[146:147], 1, s[2:3]
	v_lshlrev_b64 v[148:149], 11, v[144:145]
	v_lshl_add_u64 v[148:149], v[146:147], 0, v[148:149]
	s_mov_b64 s[18:19], 0x40000
	v_cvt_pk_bf16_f32 v62, v62, v63
	v_cvt_pk_bf16_f32 v63, v64, v65
	v_cvt_pk_bf16_f32 v64, v58, v59
	v_add_co_u32_e32 v58, vcc, s79, v148
	v_cvt_pk_bf16_f32 v70, v70, v71
	v_cvt_pk_bf16_f32 v71, v72, v73
	v_cvt_pk_bf16_f32 v72, v66, v67
	v_lshl_add_u64 v[66:67], v[148:149], 0, s[18:19]
	v_addc_co_u32_e32 v59, vcc, 0, v149, vcc
	v_cvt_pk_bf16_f32 v46, v46, v47
	v_cvt_pk_bf16_f32 v47, v48, v49
	v_cvt_pk_bf16_f32 v48, v42, v43
	v_cvt_pk_bf16_f32 v49, v44, v45
	global_store_dwordx4 v[66:67], v[46:49], off offset:256
	s_mov_b64 s[18:19], 0x48000
	v_cvt_pk_bf16_f32 v110, v110, v111
	v_add_co_u32_e32 v48, vcc, s91, v148
	v_cvt_pk_bf16_f32 v111, v112, v113
	v_cvt_pk_bf16_f32 v112, v106, v107
	v_or_b32_e32 v106, 16, v144
	v_lshl_add_u64 v[46:47], v[148:149], 0, s[18:19]
	v_addc_co_u32_e32 v49, vcc, 0, v149, vcc
	v_cvt_pk_bf16_f32 v30, v30, v31
	v_cvt_pk_bf16_f32 v31, v32, v33
	v_cvt_pk_bf16_f32 v32, v26, v27
	v_cvt_pk_bf16_f32 v33, v28, v29
	v_ashrrev_i32_e32 v107, 31, v106
	v_cvt_pk_bf16_f32 v94, v94, v95
	v_cvt_pk_bf16_f32 v95, v96, v97
	v_cvt_pk_bf16_f32 v96, v90, v91
	v_or_b32_e32 v90, 32, v144
	global_store_dwordx4 v[46:47], v[30:33], off offset:256
	s_mov_b64 s[18:19], 0x50000
	v_cvt_pk_bf16_f32 v113, v108, v109
	v_add_co_u32_e32 v32, vcc, s92, v148
	v_lshlrev_b64 v[106:107], 11, v[106:107]
	v_ashrrev_i32_e32 v91, 31, v90
	v_cvt_pk_bf16_f32 v78, v78, v79
	v_cvt_pk_bf16_f32 v79, v80, v81
	v_cvt_pk_bf16_f32 v80, v74, v75
	v_or_b32_e32 v74, 48, v144
	v_lshl_add_u64 v[30:31], v[148:149], 0, s[18:19]
	v_addc_co_u32_e32 v33, vcc, 0, v149, vcc
	v_cvt_pk_bf16_f32 v14, v14, v15
	v_cvt_pk_bf16_f32 v15, v16, v17
	v_cvt_pk_bf16_f32 v16, v10, v11
	v_cvt_pk_bf16_f32 v17, v12, v13
	global_store_dwordx4 v[148:149], v[110:113], off offset:256
	v_cvt_pk_bf16_f32 v97, v92, v93
	v_lshlrev_b64 v[90:91], 11, v[90:91]
	v_lshl_add_u64 v[110:111], v[146:147], 0, v[106:107]
	v_ashrrev_i32_e32 v75, 31, v74
	global_store_dwordx4 v[30:31], v[14:17], off offset:256
	global_store_dwordx4 v[110:111], v[94:97], off offset:256
	v_cvt_pk_bf16_f32 v81, v76, v77
	v_add_co_u32_e32 v16, vcc, 0x58000, v148
	v_lshl_add_u64 v[94:95], v[146:147], 0, v[90:91]
	v_lshlrev_b64 v[74:75], 11, v[74:75]
	s_mov_b64 s[18:19], 0x58000
	v_addc_co_u32_e32 v17, vcc, 0, v149, vcc
	v_cvt_pk_bf16_f32 v126, v126, v127
	v_cvt_pk_bf16_f32 v127, v128, v129
	v_cvt_pk_bf16_f32 v128, v122, v123
	v_cvt_pk_bf16_f32 v129, v124, v125
	v_cvt_pk_bf16_f32 v106, v118, v119
	v_cvt_pk_bf16_f32 v107, v120, v121
	v_cvt_pk_bf16_f32 v108, v114, v115
	v_cvt_pk_bf16_f32 v109, v116, v117
	v_cvt_pk_bf16_f32 v90, v102, v103
	v_cvt_pk_bf16_f32 v91, v104, v105
	v_cvt_pk_bf16_f32 v92, v98, v99
	v_cvt_pk_bf16_f32 v93, v100, v101
	global_store_dwordx4 v[94:95], v[78:81], off offset:256
	v_cvt_pk_bf16_f32 v76, v82, v83
	v_cvt_pk_bf16_f32 v77, v84, v85
	v_lshl_add_u64 v[78:79], v[146:147], 0, v[74:75]
	v_cvt_pk_bf16_f32 v74, v86, v87
	v_cvt_pk_bf16_f32 v75, v88, v89
	v_cvt_pk_bf16_f32 v73, v68, v69
	v_cvt_pk_bf16_f32 v65, v60, v61
	v_cvt_pk_bf16_f32 v42, v54, v55
	v_cvt_pk_bf16_f32 v43, v56, v57
	v_cvt_pk_bf16_f32 v44, v50, v51
	v_cvt_pk_bf16_f32 v45, v52, v53
	v_cvt_pk_bf16_f32 v26, v38, v39
	v_cvt_pk_bf16_f32 v27, v40, v41
	v_cvt_pk_bf16_f32 v28, v34, v35
	v_cvt_pk_bf16_f32 v29, v36, v37
	v_lshl_add_u64 v[14:15], v[148:149], 0, s[18:19]
	v_cvt_pk_bf16_f32 v10, v22, v23
	v_cvt_pk_bf16_f32 v11, v24, v25
	v_cvt_pk_bf16_f32 v12, v18, v19
	v_cvt_pk_bf16_f32 v13, v20, v21
	v_cvt_pk_bf16_f32 v6, v6, v7
	v_cvt_pk_bf16_f32 v7, v8, v9
	v_cvt_pk_bf16_f32 v8, v2, v3
	v_cvt_pk_bf16_f32 v9, v4, v5
	s_and_b64 vcc, exec, s[10:11]
	s_mov_b32 s45, s46
	s_mov_b32 s44, s47
	s_mov_b64 s[22:23], s[14:15]
	s_mov_b64 s[18:19], s[12:13]
	global_store_dwordx4 v[148:149], v[126:129], off
	global_store_dwordx4 v[110:111], v[106:109], off
	global_store_dwordx4 v[94:95], v[90:93], off
	global_store_dwordx4 v[78:79], v[74:77], off
	global_store_dwordx4 v[78:79], v[70:73], off offset:256
	global_store_dwordx4 v[58:59], v[62:65], off
	global_store_dwordx4 v[48:49], v[42:45], off
	global_store_dwordx4 v[32:33], v[26:29], off
	global_store_dwordx4 v[16:17], v[10:13], off
	global_store_dwordx4 v[14:15], v[6:9], off offset:256
	s_cbranch_vccz .LBB0_242
	s_waitcnt vmcnt(0)
	s_cmpk_gt_u32 s28, 0xff
	s_cbranch_scc1 .LBB0_257
	s_barrier

.LBB0_286:
	s_add_u32 s22, s18, 0xfffc0080
	s_addc_u32 s23, s19, -1
	s_add_i32 s53, 0, 0x10000
	v_add_u32_e32 v148, s53, v141
	ds_read_b128 v[144:147], v148
	ds_read_b128 v[160:163], v148 offset:1024
	ds_read_b128 v[164:167], v148 offset:2048
	ds_read_b128 v[168:171], v148 offset:3072
	s_cmp_eq_u32 s52, 12
	s_cselect_b32 s25, s11, s23
	s_cselect_b32 s24, s48, s22
	s_cselect_b32 s23, s9, s51
	s_cselect_b32 s22, s49, s50
	v_lshl_add_u64 v[148:149], s[18:19], 0, v[138:139]
	s_add_i32 m0, s3, 0xc000
	ds_read_b128 v[172:175], v143
	ds_read_b128 v[176:179], v143 offset:1024
	ds_read_b128 v[180:183], v143 offset:2048
	ds_read_b128 v[184:187], v143 offset:3072
	ds_read_b128 v[188:191], v143 offset:4096
	ds_read_b128 v[192:195], v143 offset:5120
	ds_read_b128 v[196:199], v143 offset:6144
	ds_read_b128 v[200:203], v143 offset:7168
	global_load_lds_dwordx4 v[148:149], off
	v_lshl_add_u64 v[148:149], s[18:19], 0, v[136:137]
	s_add_i32 m0, s3, 0xe000
	s_nop 0
	global_load_lds_dwordx4 v[148:149], off
	s_waitcnt lgkmcnt(8)
	s_barrier
	s_waitcnt lgkmcnt(0)
	s_waitcnt lgkmcnt(0)
	v_mfma_f32_16x16x32_bf16 v[126:129], v[144:147], v[172:175], v[126:129]
	v_mfma_f32_16x16x32_bf16 v[122:125], v[164:167], v[172:175], v[122:125]
	v_mfma_f32_16x16x32_bf16 v[118:121], v[144:147], v[180:183], v[118:121]
	v_mfma_f32_16x16x32_bf16 v[114:117], v[164:167], v[180:183], v[114:117]
	v_mfma_f32_16x16x32_bf16 v[102:105], v[144:147], v[188:191], v[102:105]
	v_mfma_f32_16x16x32_bf16 v[98:101], v[164:167], v[188:191], v[98:101]
	v_mfma_f32_16x16x32_bf16 v[86:89], v[144:147], v[196:199], v[86:89]
	v_mfma_f32_16x16x32_bf16 v[82:85], v[164:167], v[196:199], v[82:85]
	v_mfma_f32_16x16x32_bf16 v[126:129], v[160:163], v[176:179], v[126:129]
	v_mfma_f32_16x16x32_bf16 v[122:125], v[168:171], v[176:179], v[122:125]
	v_mfma_f32_16x16x32_bf16 v[118:121], v[160:163], v[184:187], v[118:121]
	v_mfma_f32_16x16x32_bf16 v[114:117], v[168:171], v[184:187], v[114:117]
	v_mfma_f32_16x16x32_bf16 v[102:105], v[160:163], v[192:195], v[102:105]
	v_mfma_f32_16x16x32_bf16 v[98:101], v[168:171], v[192:195], v[98:101]
	v_mfma_f32_16x16x32_bf16 v[86:89], v[160:163], v[200:203], v[86:89]
	v_mfma_f32_16x16x32_bf16 v[82:85], v[168:171], v[200:203], v[82:85]
	s_barrier
	s_add_i32 s56, 0, 0x14000
	v_add_u32_e32 v148, s56, v141
	s_add_i32 s53, s53, s29
	ds_read_b128 v[234:237], v148
	ds_read_b128 v[238:241], v148 offset:1024
	ds_read_b128 v[242:245], v148 offset:2048
	ds_read_b128 v[246:249], v148 offset:3072
	v_lshl_add_u64 v[148:149], s[22:23], 0, v[0:1]
	s_mov_b32 m0, s53
	v_lshl_add_u64 v[204:205], s[22:23], 0, v[134:135]
	global_load_lds_dwordx4 v[148:149], off
	s_add_i32 m0, s53, 0x2000
	s_nop 0
	global_load_lds_dwordx4 v[204:205], off
	s_barrier
	s_waitcnt lgkmcnt(0)
	s_waitcnt lgkmcnt(0)
	v_mfma_f32_16x16x32_bf16 v[110:113], v[234:237], v[172:175], v[110:113]
	v_mfma_f32_16x16x32_bf16 v[106:109], v[242:245], v[172:175], v[106:109]
	v_mfma_f32_16x16x32_bf16 v[94:97], v[234:237], v[180:183], v[94:97]
	v_mfma_f32_16x16x32_bf16 v[90:93], v[242:245], v[180:183], v[90:93]
	v_mfma_f32_16x16x32_bf16 v[78:81], v[234:237], v[188:191], v[78:81]
	v_mfma_f32_16x16x32_bf16 v[74:77], v[242:245], v[188:191], v[74:77]
	v_mfma_f32_16x16x32_bf16 v[70:73], v[234:237], v[196:199], v[70:73]
	v_mfma_f32_16x16x32_bf16 v[66:69], v[242:245], v[196:199], v[66:69]
	v_mfma_f32_16x16x32_bf16 v[110:113], v[238:241], v[176:179], v[110:113]
	v_mfma_f32_16x16x32_bf16 v[106:109], v[246:249], v[176:179], v[106:109]
	v_mfma_f32_16x16x32_bf16 v[94:97], v[238:241], v[184:187], v[94:97]
	v_mfma_f32_16x16x32_bf16 v[90:93], v[246:249], v[184:187], v[90:93]
	v_mfma_f32_16x16x32_bf16 v[78:81], v[238:241], v[192:195], v[78:81]
	v_mfma_f32_16x16x32_bf16 v[74:77], v[246:249], v[192:195], v[74:77]
	v_mfma_f32_16x16x32_bf16 v[70:73], v[238:241], v[200:203], v[70:73]
	v_mfma_f32_16x16x32_bf16 v[66:69], v[246:249], v[200:203], v[66:69]
	s_mov_b32 m0, s3
	v_lshl_add_u64 v[250:251], s[24:25], 0, v[130:131]
	s_barrier
	ds_read_b128 v[172:175], v143 offset:16384
	ds_read_b128 v[176:179], v143 offset:17408
	ds_read_b128 v[180:183], v143 offset:18432
	ds_read_b128 v[184:187], v143 offset:19456
	ds_read_b128 v[188:191], v143 offset:20480
	ds_read_b128 v[192:195], v143 offset:21504
	ds_read_b128 v[196:199], v143 offset:22528
	ds_read_b128 v[200:203], v143 offset:23552
	global_load_lds_dwordx4 v[250:251], off
	v_lshl_add_u64 v[252:253], s[24:25], 0, v[132:133]
	s_mov_b32 m0, s30
	s_nop 0
	global_load_lds_dwordx4 v[252:253], off
	s_barrier
	s_waitcnt lgkmcnt(0)
	s_waitcnt lgkmcnt(0)
	v_mfma_f32_16x16x32_bf16 v[62:65], v[144:147], v[172:175], v[62:65]
	v_mfma_f32_16x16x32_bf16 v[58:61], v[164:167], v[172:175], v[58:61]
	v_mfma_f32_16x16x32_bf16 v[54:57], v[144:147], v[180:183], v[54:57]
	v_mfma_f32_16x16x32_bf16 v[50:53], v[164:167], v[180:183], v[50:53]
	v_mfma_f32_16x16x32_bf16 v[38:41], v[144:147], v[188:191], v[38:41]
	v_mfma_f32_16x16x32_bf16 v[34:37], v[164:167], v[188:191], v[34:37]
	v_mfma_f32_16x16x32_bf16 v[22:25], v[144:147], v[196:199], v[22:25]
	v_mfma_f32_16x16x32_bf16 v[18:21], v[164:167], v[196:199], v[18:21]
	v_mfma_f32_16x16x32_bf16 v[62:65], v[160:163], v[176:179], v[62:65]
	v_mfma_f32_16x16x32_bf16 v[58:61], v[168:171], v[176:179], v[58:61]
	v_mfma_f32_16x16x32_bf16 v[54:57], v[160:163], v[184:187], v[54:57]
	v_mfma_f32_16x16x32_bf16 v[50:53], v[168:171], v[184:187], v[50:53]
	v_mfma_f32_16x16x32_bf16 v[38:41], v[160:163], v[192:195], v[38:41]
	v_mfma_f32_16x16x32_bf16 v[34:37], v[168:171], v[192:195], v[34:37]
	v_mfma_f32_16x16x32_bf16 v[22:25], v[160:163], v[200:203], v[22:25]
	v_mfma_f32_16x16x32_bf16 v[18:21], v[168:171], v[200:203], v[18:21]
	s_barrier
	s_add_u32 s54, s22, 0x40000
	s_addc_u32 s55, s23, 0
	s_add_i32 s53, s56, s29
	v_lshl_add_u64 v[144:145], s[54:55], 0, v[0:1]
	s_mov_b32 m0, s53
	s_nop 0
	global_load_lds_dwordx4 v[144:145], off
	v_lshl_add_u64 v[144:145], s[54:55], 0, v[134:135]
	s_add_i32 m0, s53, 0x2000
	s_nop 0
	global_load_lds_dwordx4 v[144:145], off
	s_waitcnt vmcnt(6)
	s_barrier
	v_mfma_f32_16x16x32_bf16 v[46:49], v[234:237], v[172:175], v[46:49]
	v_mfma_f32_16x16x32_bf16 v[42:45], v[242:245], v[172:175], v[42:45]
	v_mfma_f32_16x16x32_bf16 v[30:33], v[234:237], v[180:183], v[30:33]
	v_mfma_f32_16x16x32_bf16 v[26:29], v[242:245], v[180:183], v[26:29]
	v_mfma_f32_16x16x32_bf16 v[14:17], v[234:237], v[188:191], v[14:17]
	v_mfma_f32_16x16x32_bf16 v[10:13], v[242:245], v[188:191], v[10:13]
	v_mfma_f32_16x16x32_bf16 v[6:9], v[234:237], v[196:199], v[6:9]
	v_mfma_f32_16x16x32_bf16 v[2:5], v[242:245], v[196:199], v[2:5]
	v_mfma_f32_16x16x32_bf16 v[46:49], v[238:241], v[176:179], v[46:49]
	v_mfma_f32_16x16x32_bf16 v[42:45], v[246:249], v[176:179], v[42:45]
	v_mfma_f32_16x16x32_bf16 v[30:33], v[238:241], v[184:187], v[30:33]
	v_mfma_f32_16x16x32_bf16 v[26:29], v[246:249], v[184:187], v[26:29]
	v_mfma_f32_16x16x32_bf16 v[14:17], v[238:241], v[192:195], v[14:17]
	v_mfma_f32_16x16x32_bf16 v[10:13], v[246:249], v[192:195], v[10:13]
	v_mfma_f32_16x16x32_bf16 v[6:9], v[238:241], v[200:203], v[6:9]
	v_mfma_f32_16x16x32_bf16 v[2:5], v[246:249], v[200:203], v[2:5]
	s_add_i32 s53, 0, 0x18000
	v_add_u32_e32 v159, s53, v141
	s_barrier
	ds_read_b128 v[144:147], v159
	ds_read_b128 v[160:163], v159 offset:1024
	ds_read_b128 v[164:167], v159 offset:2048
	ds_read_b128 v[168:171], v159 offset:3072
	s_add_u32 s24, s24, 0x40000
	s_addc_u32 s25, s25, 0
	s_mov_b32 m0, s31
	v_lshl_add_u64 v[234:235], s[24:25], 0, v[130:131]
	ds_read_b128 v[172:175], v143 offset:32768
	ds_read_b128 v[176:179], v143 offset:33792
	ds_read_b128 v[180:183], v143 offset:34816
	ds_read_b128 v[184:187], v143 offset:35840
	ds_read_b128 v[188:191], v143 offset:36864
	ds_read_b128 v[192:195], v143 offset:37888
	ds_read_b128 v[196:199], v143 offset:38912
	ds_read_b128 v[200:203], v143 offset:39936
	global_load_lds_dwordx4 v[234:235], off
	v_lshl_add_u64 v[234:235], s[24:25], 0, v[132:133]
	s_mov_b32 m0, s34
	s_nop 0
	global_load_lds_dwordx4 v[234:235], off
	s_waitcnt lgkmcnt(8)
	s_barrier
	s_waitcnt lgkmcnt(0)
	s_waitcnt lgkmcnt(0)
	v_mfma_f32_16x16x32_bf16 v[126:129], v[144:147], v[172:175], v[126:129]
	v_mfma_f32_16x16x32_bf16 v[122:125], v[164:167], v[172:175], v[122:125]
	v_mfma_f32_16x16x32_bf16 v[118:121], v[144:147], v[180:183], v[118:121]
	v_mfma_f32_16x16x32_bf16 v[114:117], v[164:167], v[180:183], v[114:117]
	v_mfma_f32_16x16x32_bf16 v[102:105], v[144:147], v[188:191], v[102:105]
	v_mfma_f32_16x16x32_bf16 v[98:101], v[164:167], v[188:191], v[98:101]
	v_mfma_f32_16x16x32_bf16 v[86:89], v[144:147], v[196:199], v[86:89]
	v_mfma_f32_16x16x32_bf16 v[82:85], v[164:167], v[196:199], v[82:85]
	v_mfma_f32_16x16x32_bf16 v[126:129], v[160:163], v[176:179], v[126:129]
	v_mfma_f32_16x16x32_bf16 v[122:125], v[168:171], v[176:179], v[122:125]
	v_mfma_f32_16x16x32_bf16 v[118:121], v[160:163], v[184:187], v[118:121]
	v_mfma_f32_16x16x32_bf16 v[114:117], v[168:171], v[184:187], v[114:117]
	v_mfma_f32_16x16x32_bf16 v[102:105], v[160:163], v[192:195], v[102:105]
	v_mfma_f32_16x16x32_bf16 v[98:101], v[168:171], v[192:195], v[98:101]
	v_mfma_f32_16x16x32_bf16 v[86:89], v[160:163], v[200:203], v[86:89]
	v_mfma_f32_16x16x32_bf16 v[82:85], v[168:171], v[200:203], v[82:85]
	s_barrier
	s_add_i32 s24, 0, 0x1c000
	s_add_i32 s25, s53, s29
	v_add_u32_e32 v159, s24, v141
	v_lshl_add_u64 v[148:149], v[148:149], 0, s[20:21]
	s_mov_b32 m0, s25
	ds_read_b128 v[234:237], v159
	ds_read_b128 v[238:241], v159 offset:1024
	ds_read_b128 v[242:245], v159 offset:2048
	ds_read_b128 v[246:249], v159 offset:3072
	global_load_lds_dwordx4 v[148:149], off
	v_lshl_add_u64 v[148:149], v[204:205], 0, s[20:21]
	s_add_i32 m0, s25, 0x2000
	s_nop 0
	global_load_lds_dwordx4 v[148:149], off
	s_barrier
	s_waitcnt lgkmcnt(0)
	s_waitcnt lgkmcnt(0)
	v_mfma_f32_16x16x32_bf16 v[110:113], v[234:237], v[172:175], v[110:113]
	v_mfma_f32_16x16x32_bf16 v[106:109], v[242:245], v[172:175], v[106:109]
	v_mfma_f32_16x16x32_bf16 v[94:97], v[234:237], v[180:183], v[94:97]
	v_mfma_f32_16x16x32_bf16 v[90:93], v[242:245], v[180:183], v[90:93]
	v_mfma_f32_16x16x32_bf16 v[78:81], v[234:237], v[188:191], v[78:81]
	v_mfma_f32_16x16x32_bf16 v[74:77], v[242:245], v[188:191], v[74:77]
	v_mfma_f32_16x16x32_bf16 v[70:73], v[234:237], v[196:199], v[70:73]
	v_mfma_f32_16x16x32_bf16 v[66:69], v[242:245], v[196:199], v[66:69]
	v_mfma_f32_16x16x32_bf16 v[110:113], v[238:241], v[176:179], v[110:113]
	v_mfma_f32_16x16x32_bf16 v[106:109], v[246:249], v[176:179], v[106:109]
	v_mfma_f32_16x16x32_bf16 v[94:97], v[238:241], v[184:187], v[94:97]
	v_mfma_f32_16x16x32_bf16 v[90:93], v[246:249], v[184:187], v[90:93]
	v_mfma_f32_16x16x32_bf16 v[78:81], v[238:241], v[192:195], v[78:81]
	v_mfma_f32_16x16x32_bf16 v[74:77], v[246:249], v[192:195], v[74:77]
	v_mfma_f32_16x16x32_bf16 v[70:73], v[238:241], v[200:203], v[70:73]
	v_mfma_f32_16x16x32_bf16 v[66:69], v[246:249], v[200:203], v[66:69]
	s_mov_b32 m0, s35
	v_lshl_add_u64 v[148:149], v[250:251], 0, s[20:21]
	s_barrier
	ds_read_b128 v[172:175], v143 offset:49152
	ds_read_b128 v[176:179], v143 offset:50176
	ds_read_b128 v[180:183], v143 offset:51200
	ds_read_b128 v[184:187], v143 offset:52224
	ds_read_b128 v[188:191], v143 offset:53248
	ds_read_b128 v[192:195], v143 offset:54272
	ds_read_b128 v[196:199], v143 offset:55296
	ds_read_b128 v[200:203], v143 offset:56320
	global_load_lds_dwordx4 v[148:149], off
	v_lshl_add_u64 v[148:149], v[252:253], 0, s[20:21]
	s_mov_b32 m0, s38
	s_nop 0
	global_load_lds_dwordx4 v[148:149], off
	s_barrier
	s_waitcnt lgkmcnt(0)
	s_waitcnt lgkmcnt(0)
	v_mfma_f32_16x16x32_bf16 v[62:65], v[144:147], v[172:175], v[62:65]
	v_mfma_f32_16x16x32_bf16 v[58:61], v[164:167], v[172:175], v[58:61]
	v_mfma_f32_16x16x32_bf16 v[54:57], v[144:147], v[180:183], v[54:57]
	v_mfma_f32_16x16x32_bf16 v[50:53], v[164:167], v[180:183], v[50:53]
	v_mfma_f32_16x16x32_bf16 v[38:41], v[144:147], v[188:191], v[38:41]
	v_mfma_f32_16x16x32_bf16 v[34:37], v[164:167], v[188:191], v[34:37]
	v_mfma_f32_16x16x32_bf16 v[22:25], v[144:147], v[196:199], v[22:25]
	v_mfma_f32_16x16x32_bf16 v[18:21], v[164:167], v[196:199], v[18:21]
	v_mfma_f32_16x16x32_bf16 v[62:65], v[160:163], v[176:179], v[62:65]
	v_mfma_f32_16x16x32_bf16 v[58:61], v[168:171], v[176:179], v[58:61]
	v_mfma_f32_16x16x32_bf16 v[54:57], v[160:163], v[184:187], v[54:57]
	v_mfma_f32_16x16x32_bf16 v[50:53], v[168:171], v[184:187], v[50:53]
	v_mfma_f32_16x16x32_bf16 v[38:41], v[160:163], v[192:195], v[38:41]
	v_mfma_f32_16x16x32_bf16 v[34:37], v[168:171], v[192:195], v[34:37]
	v_mfma_f32_16x16x32_bf16 v[22:25], v[160:163], v[200:203], v[22:25]
	v_mfma_f32_16x16x32_bf16 v[18:21], v[168:171], v[200:203], v[18:21]
	s_barrier
	s_add_u32 s22, s22, 0x40080
	s_addc_u32 s23, s23, 0
	s_add_i32 s24, s24, s29
	v_lshl_add_u64 v[144:145], s[22:23], 0, v[0:1]
	s_mov_b32 m0, s24
	s_nop 0
	global_load_lds_dwordx4 v[144:145], off
	v_lshl_add_u64 v[144:145], s[22:23], 0, v[134:135]
	s_add_i32 m0, s24, 0x2000
	s_nop 0
	global_load_lds_dwordx4 v[144:145], off
	s_waitcnt vmcnt(6)
	s_barrier
	v_mfma_f32_16x16x32_bf16 v[46:49], v[234:237], v[172:175], v[46:49]
	v_mfma_f32_16x16x32_bf16 v[42:45], v[242:245], v[172:175], v[42:45]
	v_mfma_f32_16x16x32_bf16 v[30:33], v[234:237], v[180:183], v[30:33]
	v_mfma_f32_16x16x32_bf16 v[26:29], v[242:245], v[180:183], v[26:29]
	v_mfma_f32_16x16x32_bf16 v[14:17], v[234:237], v[188:191], v[14:17]
	v_mfma_f32_16x16x32_bf16 v[10:13], v[242:245], v[188:191], v[10:13]
	v_mfma_f32_16x16x32_bf16 v[6:9], v[234:237], v[196:199], v[6:9]
	v_mfma_f32_16x16x32_bf16 v[2:5], v[242:245], v[196:199], v[2:5]
	v_mfma_f32_16x16x32_bf16 v[46:49], v[238:241], v[176:179], v[46:49]
	v_mfma_f32_16x16x32_bf16 v[42:45], v[246:249], v[176:179], v[42:45]
	v_mfma_f32_16x16x32_bf16 v[30:33], v[238:241], v[184:187], v[30:33]
	v_mfma_f32_16x16x32_bf16 v[26:29], v[246:249], v[184:187], v[26:29]
	v_mfma_f32_16x16x32_bf16 v[14:17], v[238:241], v[192:195], v[14:17]
	v_mfma_f32_16x16x32_bf16 v[10:13], v[246:249], v[192:195], v[10:13]
	v_mfma_f32_16x16x32_bf16 v[6:9], v[238:241], v[200:203], v[6:9]
	v_mfma_f32_16x16x32_bf16 v[2:5], v[246:249], v[200:203], v[2:5]
	s_add_i32 s52, s52, 2
	s_add_u32 s50, s50, 0x100
	s_addc_u32 s51, s51, 0
	s_add_u32 s18, s18, 0x100
	s_addc_u32 s19, s19, 0
	s_cmp_gt_u32 s52, 13
	s_barrier
	s_cbranch_scc0 .LBB0_286
	v_lshl_add_u32 v144, s2, 8, v140
	v_lshl_or_b32 v146, s43, 8, v142
	v_ashrrev_i32_e32 v147, 31, v146
	v_ashrrev_i32_e32 v145, 31, v144
	v_lshl_add_u64 v[146:147], v[146:147], 1, s[46:47]
	v_lshlrev_b64 v[148:149], 11, v[144:145]
	v_lshl_add_u64 v[148:149], v[146:147], 0, v[148:149]
	s_mov_b64 s[18:19], 0x40000
	v_cvt_pk_bf16_f32 v62, v62, v63
	v_cvt_pk_bf16_f32 v63, v64, v65
	v_cvt_pk_bf16_f32 v64, v58, v59
	v_add_co_u32_e32 v58, vcc, s79, v148
	v_cvt_pk_bf16_f32 v70, v70, v71
	v_cvt_pk_bf16_f32 v71, v72, v73
	v_cvt_pk_bf16_f32 v72, v66, v67
	v_lshl_add_u64 v[66:67], v[148:149], 0, s[18:19]
	v_addc_co_u32_e32 v59, vcc, 0, v149, vcc
	v_cvt_pk_bf16_f32 v46, v46, v47
	v_cvt_pk_bf16_f32 v47, v48, v49
	v_cvt_pk_bf16_f32 v48, v42, v43
	v_cvt_pk_bf16_f32 v49, v44, v45
	global_store_dwordx4 v[66:67], v[46:49], off offset:256
	s_mov_b64 s[18:19], 0x48000
	v_cvt_pk_bf16_f32 v110, v110, v111
	v_add_co_u32_e32 v48, vcc, s91, v148
	v_cvt_pk_bf16_f32 v111, v112, v113
	v_cvt_pk_bf16_f32 v112, v106, v107
	v_or_b32_e32 v106, 16, v144
	v_lshl_add_u64 v[46:47], v[148:149], 0, s[18:19]
	v_addc_co_u32_e32 v49, vcc, 0, v149, vcc
	v_cvt_pk_bf16_f32 v30, v30, v31
	v_cvt_pk_bf16_f32 v31, v32, v33
	v_cvt_pk_bf16_f32 v32, v26, v27
	v_cvt_pk_bf16_f32 v33, v28, v29
	v_ashrrev_i32_e32 v107, 31, v106
	v_cvt_pk_bf16_f32 v94, v94, v95
	v_cvt_pk_bf16_f32 v95, v96, v97
	v_cvt_pk_bf16_f32 v96, v90, v91
	v_or_b32_e32 v90, 32, v144
	global_store_dwordx4 v[46:47], v[30:33], off offset:256
	s_mov_b64 s[18:19], 0x50000
	v_cvt_pk_bf16_f32 v113, v108, v109
	v_add_co_u32_e32 v32, vcc, s92, v148
	v_lshlrev_b64 v[106:107], 11, v[106:107]
	v_ashrrev_i32_e32 v91, 31, v90
	v_cvt_pk_bf16_f32 v78, v78, v79
	v_cvt_pk_bf16_f32 v79, v80, v81
	v_cvt_pk_bf16_f32 v80, v74, v75
	v_or_b32_e32 v74, 48, v144
	v_lshl_add_u64 v[30:31], v[148:149], 0, s[18:19]
	v_addc_co_u32_e32 v33, vcc, 0, v149, vcc
	v_cvt_pk_bf16_f32 v14, v14, v15
	v_cvt_pk_bf16_f32 v15, v16, v17
	v_cvt_pk_bf16_f32 v16, v10, v11
	v_cvt_pk_bf16_f32 v17, v12, v13
	global_store_dwordx4 v[148:149], v[110:113], off offset:256
	v_cvt_pk_bf16_f32 v97, v92, v93
	v_lshlrev_b64 v[90:91], 11, v[90:91]
	v_lshl_add_u64 v[110:111], v[146:147], 0, v[106:107]
	v_ashrrev_i32_e32 v75, 31, v74
	global_store_dwordx4 v[30:31], v[14:17], off offset:256
	global_store_dwordx4 v[110:111], v[94:97], off offset:256
	v_cvt_pk_bf16_f32 v81, v76, v77
	v_add_co_u32_e32 v16, vcc, 0x58000, v148
	v_lshl_add_u64 v[94:95], v[146:147], 0, v[90:91]
	v_lshlrev_b64 v[74:75], 11, v[74:75]
	s_mov_b64 s[18:19], 0x58000
	v_addc_co_u32_e32 v17, vcc, 0, v149, vcc
	v_readlane_b32 s54, v255, 3
	v_cvt_pk_bf16_f32 v126, v126, v127
	v_cvt_pk_bf16_f32 v127, v128, v129
	v_cvt_pk_bf16_f32 v128, v122, v123
	v_cvt_pk_bf16_f32 v129, v124, v125
	v_cvt_pk_bf16_f32 v106, v118, v119
	v_cvt_pk_bf16_f32 v107, v120, v121
	v_cvt_pk_bf16_f32 v108, v114, v115
	v_cvt_pk_bf16_f32 v109, v116, v117
	v_cvt_pk_bf16_f32 v90, v102, v103
	v_cvt_pk_bf16_f32 v91, v104, v105
	v_cvt_pk_bf16_f32 v92, v98, v99
	v_cvt_pk_bf16_f32 v93, v100, v101
	global_store_dwordx4 v[94:95], v[78:81], off offset:256
	v_cvt_pk_bf16_f32 v76, v82, v83
	v_cvt_pk_bf16_f32 v77, v84, v85
	v_lshl_add_u64 v[78:79], v[146:147], 0, v[74:75]
	v_cvt_pk_bf16_f32 v74, v86, v87
	v_cvt_pk_bf16_f32 v75, v88, v89
	v_cvt_pk_bf16_f32 v73, v68, v69
	v_cvt_pk_bf16_f32 v65, v60, v61
	v_cvt_pk_bf16_f32 v42, v54, v55
	v_cvt_pk_bf16_f32 v43, v56, v57
	v_cvt_pk_bf16_f32 v44, v50, v51
	v_cvt_pk_bf16_f32 v45, v52, v53
	v_cvt_pk_bf16_f32 v26, v38, v39
	v_cvt_pk_bf16_f32 v27, v40, v41
	v_cvt_pk_bf16_f32 v28, v34, v35
	v_cvt_pk_bf16_f32 v29, v36, v37
	v_lshl_add_u64 v[14:15], v[148:149], 0, s[18:19]
	v_cvt_pk_bf16_f32 v10, v22, v23
	v_cvt_pk_bf16_f32 v11, v24, v25
	v_cvt_pk_bf16_f32 v12, v18, v19
	v_cvt_pk_bf16_f32 v13, v20, v21
	v_cvt_pk_bf16_f32 v6, v6, v7
	v_cvt_pk_bf16_f32 v7, v8, v9
	v_cvt_pk_bf16_f32 v8, v2, v3
	v_cvt_pk_bf16_f32 v9, v4, v5
	s_and_b64 vcc, exec, s[40:41]
	s_mov_b32 s43, s8
	s_mov_b32 s2, s10
	s_mov_b64 s[18:19], s[14:15]
	s_mov_b64 s[22:23], s[12:13]
	v_readlane_b32 s55, v255, 4
	s_mov_b32 s56, s66
	global_store_dwordx4 v[148:149], v[126:129], off
	global_store_dwordx4 v[110:111], v[106:109], off
	global_store_dwordx4 v[94:95], v[90:93], off
	global_store_dwordx4 v[78:79], v[74:77], off
	global_store_dwordx4 v[78:79], v[70:73], off offset:256
	global_store_dwordx4 v[58:59], v[62:65], off
	global_store_dwordx4 v[48:49], v[42:45], off
	global_store_dwordx4 v[32:33], v[26:29], off
	global_store_dwordx4 v[16:17], v[10:13], off
	global_store_dwordx4 v[14:15], v[6:9], off offset:256
	s_cbranch_vccz .LBB0_279
	s_waitcnt vmcnt(0)
	s_cmpk_gt_u32 s1, 0xff
	s_cbranch_scc1 .LBB0_290
	s_barrier

.LBB0_672:
	s_add_u32 s22, s18, 0xfffc0080
	s_addc_u32 s23, s19, -1
	s_add_i32 s53, 0, 0x10000
	v_add_u32_e32 v148, s53, v141
	ds_read_b128 v[144:147], v148
	ds_read_b128 v[160:163], v148 offset:1024
	ds_read_b128 v[164:167], v148 offset:2048
	ds_read_b128 v[168:171], v148 offset:3072
	s_cmp_eq_u32 s52, 12
	s_cselect_b32 s25, s11, s23
	s_cselect_b32 s24, s48, s22
	s_cselect_b32 s23, s9, s51
	s_cselect_b32 s22, s49, s50
	v_lshl_add_u64 v[148:149], s[18:19], 0, v[138:139]
	s_add_i32 m0, s3, 0xc000
	ds_read_b128 v[172:175], v143
	ds_read_b128 v[176:179], v143 offset:1024
	ds_read_b128 v[180:183], v143 offset:2048
	ds_read_b128 v[184:187], v143 offset:3072
	ds_read_b128 v[188:191], v143 offset:4096
	ds_read_b128 v[192:195], v143 offset:5120
	ds_read_b128 v[196:199], v143 offset:6144
	ds_read_b128 v[200:203], v143 offset:7168
	global_load_lds_dwordx4 v[148:149], off
	v_lshl_add_u64 v[148:149], s[18:19], 0, v[136:137]
	s_add_i32 m0, s3, 0xe000
	s_nop 0
	global_load_lds_dwordx4 v[148:149], off
	s_waitcnt lgkmcnt(8)
	s_barrier
	s_waitcnt lgkmcnt(0)
	s_waitcnt lgkmcnt(0)
	v_mfma_f32_16x16x32_bf16 v[126:129], v[144:147], v[172:175], v[126:129]
	v_mfma_f32_16x16x32_bf16 v[122:125], v[164:167], v[172:175], v[122:125]
	v_mfma_f32_16x16x32_bf16 v[118:121], v[144:147], v[180:183], v[118:121]
	v_mfma_f32_16x16x32_bf16 v[114:117], v[164:167], v[180:183], v[114:117]
	v_mfma_f32_16x16x32_bf16 v[102:105], v[144:147], v[188:191], v[102:105]
	v_mfma_f32_16x16x32_bf16 v[98:101], v[164:167], v[188:191], v[98:101]
	v_mfma_f32_16x16x32_bf16 v[86:89], v[144:147], v[196:199], v[86:89]
	v_mfma_f32_16x16x32_bf16 v[82:85], v[164:167], v[196:199], v[82:85]
	v_mfma_f32_16x16x32_bf16 v[126:129], v[160:163], v[176:179], v[126:129]
	v_mfma_f32_16x16x32_bf16 v[122:125], v[168:171], v[176:179], v[122:125]
	v_mfma_f32_16x16x32_bf16 v[118:121], v[160:163], v[184:187], v[118:121]
	v_mfma_f32_16x16x32_bf16 v[114:117], v[168:171], v[184:187], v[114:117]
	v_mfma_f32_16x16x32_bf16 v[102:105], v[160:163], v[192:195], v[102:105]
	v_mfma_f32_16x16x32_bf16 v[98:101], v[168:171], v[192:195], v[98:101]
	v_mfma_f32_16x16x32_bf16 v[86:89], v[160:163], v[200:203], v[86:89]
	v_mfma_f32_16x16x32_bf16 v[82:85], v[168:171], v[200:203], v[82:85]
	s_barrier
	s_add_i32 s56, 0, 0x14000
	v_add_u32_e32 v148, s56, v141
	s_add_i32 s53, s53, s28
	ds_read_b128 v[234:237], v148
	ds_read_b128 v[238:241], v148 offset:1024
	ds_read_b128 v[242:245], v148 offset:2048
	ds_read_b128 v[246:249], v148 offset:3072
	v_lshl_add_u64 v[148:149], s[22:23], 0, v[0:1]
	s_mov_b32 m0, s53
	v_lshl_add_u64 v[204:205], s[22:23], 0, v[130:131]
	global_load_lds_dwordx4 v[148:149], off
	s_add_i32 m0, s53, 0x2000
	s_nop 0
	global_load_lds_dwordx4 v[204:205], off
	s_barrier
	s_waitcnt lgkmcnt(0)
	s_waitcnt lgkmcnt(0)
	v_mfma_f32_16x16x32_bf16 v[110:113], v[234:237], v[172:175], v[110:113]
	v_mfma_f32_16x16x32_bf16 v[106:109], v[242:245], v[172:175], v[106:109]
	v_mfma_f32_16x16x32_bf16 v[94:97], v[234:237], v[180:183], v[94:97]
	v_mfma_f32_16x16x32_bf16 v[90:93], v[242:245], v[180:183], v[90:93]
	v_mfma_f32_16x16x32_bf16 v[78:81], v[234:237], v[188:191], v[78:81]
	v_mfma_f32_16x16x32_bf16 v[74:77], v[242:245], v[188:191], v[74:77]
	v_mfma_f32_16x16x32_bf16 v[70:73], v[234:237], v[196:199], v[70:73]
	v_mfma_f32_16x16x32_bf16 v[66:69], v[242:245], v[196:199], v[66:69]
	v_mfma_f32_16x16x32_bf16 v[110:113], v[238:241], v[176:179], v[110:113]
	v_mfma_f32_16x16x32_bf16 v[106:109], v[246:249], v[176:179], v[106:109]
	v_mfma_f32_16x16x32_bf16 v[94:97], v[238:241], v[184:187], v[94:97]
	v_mfma_f32_16x16x32_bf16 v[90:93], v[246:249], v[184:187], v[90:93]
	v_mfma_f32_16x16x32_bf16 v[78:81], v[238:241], v[192:195], v[78:81]
	v_mfma_f32_16x16x32_bf16 v[74:77], v[246:249], v[192:195], v[74:77]
	v_mfma_f32_16x16x32_bf16 v[70:73], v[238:241], v[200:203], v[70:73]
	v_mfma_f32_16x16x32_bf16 v[66:69], v[246:249], v[200:203], v[66:69]
	s_mov_b32 m0, s3
	v_lshl_add_u64 v[250:251], s[24:25], 0, v[134:135]
	s_barrier
	ds_read_b128 v[172:175], v143 offset:16384
	ds_read_b128 v[176:179], v143 offset:17408
	ds_read_b128 v[180:183], v143 offset:18432
	ds_read_b128 v[184:187], v143 offset:19456
	ds_read_b128 v[188:191], v143 offset:20480
	ds_read_b128 v[192:195], v143 offset:21504
	ds_read_b128 v[196:199], v143 offset:22528
	ds_read_b128 v[200:203], v143 offset:23552
	global_load_lds_dwordx4 v[250:251], off
	v_lshl_add_u64 v[252:253], s[24:25], 0, v[132:133]
	s_mov_b32 m0, s30
	s_nop 0
	global_load_lds_dwordx4 v[252:253], off
	s_barrier
	s_waitcnt lgkmcnt(0)
	s_waitcnt lgkmcnt(0)
	v_mfma_f32_16x16x32_bf16 v[62:65], v[144:147], v[172:175], v[62:65]
	v_mfma_f32_16x16x32_bf16 v[58:61], v[164:167], v[172:175], v[58:61]
	v_mfma_f32_16x16x32_bf16 v[54:57], v[144:147], v[180:183], v[54:57]
	v_mfma_f32_16x16x32_bf16 v[50:53], v[164:167], v[180:183], v[50:53]
	v_mfma_f32_16x16x32_bf16 v[38:41], v[144:147], v[188:191], v[38:41]
	v_mfma_f32_16x16x32_bf16 v[34:37], v[164:167], v[188:191], v[34:37]
	v_mfma_f32_16x16x32_bf16 v[22:25], v[144:147], v[196:199], v[22:25]
	v_mfma_f32_16x16x32_bf16 v[18:21], v[164:167], v[196:199], v[18:21]
	v_mfma_f32_16x16x32_bf16 v[62:65], v[160:163], v[176:179], v[62:65]
	v_mfma_f32_16x16x32_bf16 v[58:61], v[168:171], v[176:179], v[58:61]
	v_mfma_f32_16x16x32_bf16 v[54:57], v[160:163], v[184:187], v[54:57]
	v_mfma_f32_16x16x32_bf16 v[50:53], v[168:171], v[184:187], v[50:53]
	v_mfma_f32_16x16x32_bf16 v[38:41], v[160:163], v[192:195], v[38:41]
	v_mfma_f32_16x16x32_bf16 v[34:37], v[168:171], v[192:195], v[34:37]
	v_mfma_f32_16x16x32_bf16 v[22:25], v[160:163], v[200:203], v[22:25]
	v_mfma_f32_16x16x32_bf16 v[18:21], v[168:171], v[200:203], v[18:21]
	s_barrier
	s_add_u32 s54, s22, 0x40000
	s_addc_u32 s55, s23, 0
	s_add_i32 s53, s56, s28
	v_lshl_add_u64 v[144:145], s[54:55], 0, v[0:1]
	s_mov_b32 m0, s53
	s_nop 0
	global_load_lds_dwordx4 v[144:145], off
	v_lshl_add_u64 v[144:145], s[54:55], 0, v[130:131]
	s_add_i32 m0, s53, 0x2000
	s_nop 0
	global_load_lds_dwordx4 v[144:145], off
	s_waitcnt vmcnt(6)
	s_barrier
	v_mfma_f32_16x16x32_bf16 v[46:49], v[234:237], v[172:175], v[46:49]
	v_mfma_f32_16x16x32_bf16 v[42:45], v[242:245], v[172:175], v[42:45]
	v_mfma_f32_16x16x32_bf16 v[30:33], v[234:237], v[180:183], v[30:33]
	v_mfma_f32_16x16x32_bf16 v[26:29], v[242:245], v[180:183], v[26:29]
	v_mfma_f32_16x16x32_bf16 v[14:17], v[234:237], v[188:191], v[14:17]
	v_mfma_f32_16x16x32_bf16 v[10:13], v[242:245], v[188:191], v[10:13]
	v_mfma_f32_16x16x32_bf16 v[6:9], v[234:237], v[196:199], v[6:9]
	v_mfma_f32_16x16x32_bf16 v[2:5], v[242:245], v[196:199], v[2:5]
	v_mfma_f32_16x16x32_bf16 v[46:49], v[238:241], v[176:179], v[46:49]
	v_mfma_f32_16x16x32_bf16 v[42:45], v[246:249], v[176:179], v[42:45]
	v_mfma_f32_16x16x32_bf16 v[30:33], v[238:241], v[184:187], v[30:33]
	v_mfma_f32_16x16x32_bf16 v[26:29], v[246:249], v[184:187], v[26:29]
	v_mfma_f32_16x16x32_bf16 v[14:17], v[238:241], v[192:195], v[14:17]
	v_mfma_f32_16x16x32_bf16 v[10:13], v[246:249], v[192:195], v[10:13]
	v_mfma_f32_16x16x32_bf16 v[6:9], v[238:241], v[200:203], v[6:9]
	v_mfma_f32_16x16x32_bf16 v[2:5], v[246:249], v[200:203], v[2:5]
	s_add_i32 s53, 0, 0x18000
	v_add_u32_e32 v159, s53, v141
	s_barrier
	ds_read_b128 v[144:147], v159
	ds_read_b128 v[160:163], v159 offset:1024
	ds_read_b128 v[164:167], v159 offset:2048
	ds_read_b128 v[168:171], v159 offset:3072
	s_add_u32 s24, s24, 0x40000
	s_addc_u32 s25, s25, 0
	s_mov_b32 m0, s31
	v_lshl_add_u64 v[234:235], s[24:25], 0, v[134:135]
	ds_read_b128 v[172:175], v143 offset:32768
	ds_read_b128 v[176:179], v143 offset:33792
	ds_read_b128 v[180:183], v143 offset:34816
	ds_read_b128 v[184:187], v143 offset:35840
	ds_read_b128 v[188:191], v143 offset:36864
	ds_read_b128 v[192:195], v143 offset:37888
	ds_read_b128 v[196:199], v143 offset:38912
	ds_read_b128 v[200:203], v143 offset:39936
	global_load_lds_dwordx4 v[234:235], off
	v_lshl_add_u64 v[234:235], s[24:25], 0, v[132:133]
	s_mov_b32 m0, s34
	s_nop 0
	global_load_lds_dwordx4 v[234:235], off
	s_waitcnt lgkmcnt(8)
	s_barrier
	s_waitcnt lgkmcnt(0)
	s_waitcnt lgkmcnt(0)
	v_mfma_f32_16x16x32_bf16 v[126:129], v[144:147], v[172:175], v[126:129]
	v_mfma_f32_16x16x32_bf16 v[122:125], v[164:167], v[172:175], v[122:125]
	v_mfma_f32_16x16x32_bf16 v[118:121], v[144:147], v[180:183], v[118:121]
	v_mfma_f32_16x16x32_bf16 v[114:117], v[164:167], v[180:183], v[114:117]
	v_mfma_f32_16x16x32_bf16 v[102:105], v[144:147], v[188:191], v[102:105]
	v_mfma_f32_16x16x32_bf16 v[98:101], v[164:167], v[188:191], v[98:101]
	v_mfma_f32_16x16x32_bf16 v[86:89], v[144:147], v[196:199], v[86:89]
	v_mfma_f32_16x16x32_bf16 v[82:85], v[164:167], v[196:199], v[82:85]
	v_mfma_f32_16x16x32_bf16 v[126:129], v[160:163], v[176:179], v[126:129]
	v_mfma_f32_16x16x32_bf16 v[122:125], v[168:171], v[176:179], v[122:125]
	v_mfma_f32_16x16x32_bf16 v[118:121], v[160:163], v[184:187], v[118:121]
	v_mfma_f32_16x16x32_bf16 v[114:117], v[168:171], v[184:187], v[114:117]
	v_mfma_f32_16x16x32_bf16 v[102:105], v[160:163], v[192:195], v[102:105]
	v_mfma_f32_16x16x32_bf16 v[98:101], v[168:171], v[192:195], v[98:101]
	v_mfma_f32_16x16x32_bf16 v[86:89], v[160:163], v[200:203], v[86:89]
	v_mfma_f32_16x16x32_bf16 v[82:85], v[168:171], v[200:203], v[82:85]
	s_barrier
	s_add_i32 s24, 0, 0x1c000
	s_add_i32 s25, s53, s28
	v_add_u32_e32 v159, s24, v141
	v_lshl_add_u64 v[148:149], v[148:149], 0, s[20:21]
	s_mov_b32 m0, s25
	ds_read_b128 v[234:237], v159
	ds_read_b128 v[238:241], v159 offset:1024
	ds_read_b128 v[242:245], v159 offset:2048
	ds_read_b128 v[246:249], v159 offset:3072
	global_load_lds_dwordx4 v[148:149], off
	v_lshl_add_u64 v[148:149], v[204:205], 0, s[20:21]
	s_add_i32 m0, s25, 0x2000
	s_nop 0
	global_load_lds_dwordx4 v[148:149], off
	s_barrier
	s_waitcnt lgkmcnt(0)
	s_waitcnt lgkmcnt(0)
	v_mfma_f32_16x16x32_bf16 v[110:113], v[234:237], v[172:175], v[110:113]
	v_mfma_f32_16x16x32_bf16 v[106:109], v[242:245], v[172:175], v[106:109]
	v_mfma_f32_16x16x32_bf16 v[94:97], v[234:237], v[180:183], v[94:97]
	v_mfma_f32_16x16x32_bf16 v[90:93], v[242:245], v[180:183], v[90:93]
	v_mfma_f32_16x16x32_bf16 v[78:81], v[234:237], v[188:191], v[78:81]
	v_mfma_f32_16x16x32_bf16 v[74:77], v[242:245], v[188:191], v[74:77]
	v_mfma_f32_16x16x32_bf16 v[70:73], v[234:237], v[196:199], v[70:73]
	v_mfma_f32_16x16x32_bf16 v[66:69], v[242:245], v[196:199], v[66:69]
	v_mfma_f32_16x16x32_bf16 v[110:113], v[238:241], v[176:179], v[110:113]
	v_mfma_f32_16x16x32_bf16 v[106:109], v[246:249], v[176:179], v[106:109]
	v_mfma_f32_16x16x32_bf16 v[94:97], v[238:241], v[184:187], v[94:97]
	v_mfma_f32_16x16x32_bf16 v[90:93], v[246:249], v[184:187], v[90:93]
	v_mfma_f32_16x16x32_bf16 v[78:81], v[238:241], v[192:195], v[78:81]
	v_mfma_f32_16x16x32_bf16 v[74:77], v[246:249], v[192:195], v[74:77]
	v_mfma_f32_16x16x32_bf16 v[70:73], v[238:241], v[200:203], v[70:73]
	v_mfma_f32_16x16x32_bf16 v[66:69], v[246:249], v[200:203], v[66:69]
	s_mov_b32 m0, s35
	v_lshl_add_u64 v[148:149], v[250:251], 0, s[20:21]
	s_barrier
	ds_read_b128 v[172:175], v143 offset:49152
	ds_read_b128 v[176:179], v143 offset:50176
	ds_read_b128 v[180:183], v143 offset:51200
	ds_read_b128 v[184:187], v143 offset:52224
	ds_read_b128 v[188:191], v143 offset:53248
	ds_read_b128 v[192:195], v143 offset:54272
	ds_read_b128 v[196:199], v143 offset:55296
	ds_read_b128 v[200:203], v143 offset:56320
	global_load_lds_dwordx4 v[148:149], off
	v_lshl_add_u64 v[148:149], v[252:253], 0, s[20:21]
	s_mov_b32 m0, s38
	s_nop 0
	global_load_lds_dwordx4 v[148:149], off
	s_barrier
	s_waitcnt lgkmcnt(0)
	s_waitcnt lgkmcnt(0)
	v_mfma_f32_16x16x32_bf16 v[62:65], v[144:147], v[172:175], v[62:65]
	v_mfma_f32_16x16x32_bf16 v[58:61], v[164:167], v[172:175], v[58:61]
	v_mfma_f32_16x16x32_bf16 v[54:57], v[144:147], v[180:183], v[54:57]
	v_mfma_f32_16x16x32_bf16 v[50:53], v[164:167], v[180:183], v[50:53]
	v_mfma_f32_16x16x32_bf16 v[38:41], v[144:147], v[188:191], v[38:41]
	v_mfma_f32_16x16x32_bf16 v[34:37], v[164:167], v[188:191], v[34:37]
	v_mfma_f32_16x16x32_bf16 v[22:25], v[144:147], v[196:199], v[22:25]
	v_mfma_f32_16x16x32_bf16 v[18:21], v[164:167], v[196:199], v[18:21]
	v_mfma_f32_16x16x32_bf16 v[62:65], v[160:163], v[176:179], v[62:65]
	v_mfma_f32_16x16x32_bf16 v[58:61], v[168:171], v[176:179], v[58:61]
	v_mfma_f32_16x16x32_bf16 v[54:57], v[160:163], v[184:187], v[54:57]
	v_mfma_f32_16x16x32_bf16 v[50:53], v[168:171], v[184:187], v[50:53]
	v_mfma_f32_16x16x32_bf16 v[38:41], v[160:163], v[192:195], v[38:41]
	v_mfma_f32_16x16x32_bf16 v[34:37], v[168:171], v[192:195], v[34:37]
	v_mfma_f32_16x16x32_bf16 v[22:25], v[160:163], v[200:203], v[22:25]
	v_mfma_f32_16x16x32_bf16 v[18:21], v[168:171], v[200:203], v[18:21]
	s_barrier
	s_add_u32 s22, s22, 0x40080
	s_addc_u32 s23, s23, 0
	s_add_i32 s24, s24, s28
	v_lshl_add_u64 v[144:145], s[22:23], 0, v[0:1]
	s_mov_b32 m0, s24
	s_nop 0
	global_load_lds_dwordx4 v[144:145], off
	v_lshl_add_u64 v[144:145], s[22:23], 0, v[130:131]
	s_add_i32 m0, s24, 0x2000
	s_nop 0
	global_load_lds_dwordx4 v[144:145], off
	s_waitcnt vmcnt(6)
	s_barrier
	v_mfma_f32_16x16x32_bf16 v[46:49], v[234:237], v[172:175], v[46:49]
	v_mfma_f32_16x16x32_bf16 v[42:45], v[242:245], v[172:175], v[42:45]
	v_mfma_f32_16x16x32_bf16 v[30:33], v[234:237], v[180:183], v[30:33]
	v_mfma_f32_16x16x32_bf16 v[26:29], v[242:245], v[180:183], v[26:29]
	v_mfma_f32_16x16x32_bf16 v[14:17], v[234:237], v[188:191], v[14:17]
	v_mfma_f32_16x16x32_bf16 v[10:13], v[242:245], v[188:191], v[10:13]
	v_mfma_f32_16x16x32_bf16 v[6:9], v[234:237], v[196:199], v[6:9]
	v_mfma_f32_16x16x32_bf16 v[2:5], v[242:245], v[196:199], v[2:5]
	v_mfma_f32_16x16x32_bf16 v[46:49], v[238:241], v[176:179], v[46:49]
	v_mfma_f32_16x16x32_bf16 v[42:45], v[246:249], v[176:179], v[42:45]
	v_mfma_f32_16x16x32_bf16 v[30:33], v[238:241], v[184:187], v[30:33]
	v_mfma_f32_16x16x32_bf16 v[26:29], v[246:249], v[184:187], v[26:29]
	v_mfma_f32_16x16x32_bf16 v[14:17], v[238:241], v[192:195], v[14:17]
	v_mfma_f32_16x16x32_bf16 v[10:13], v[246:249], v[192:195], v[10:13]
	v_mfma_f32_16x16x32_bf16 v[6:9], v[238:241], v[200:203], v[6:9]
	v_mfma_f32_16x16x32_bf16 v[2:5], v[246:249], v[200:203], v[2:5]
	s_add_i32 s52, s52, 2
	s_add_u32 s50, s50, 0x100
	s_addc_u32 s51, s51, 0
	s_add_u32 s18, s18, 0x100
	s_addc_u32 s19, s19, 0
	s_cmp_gt_u32 s52, 13
	s_barrier
	s_cbranch_scc0 .LBB0_672
	v_lshl_or_b32 v144, s43, 8, v142
	v_lshl_add_u32 v148, s2, 8, v140
	v_ashrrev_i32_e32 v145, 31, v144
	v_lshl_add_u64 v[144:145], v[144:145], 1, s[46:47]
	v_cvt_pk_bf16_f32 v70, v70, v71
	v_cvt_pk_bf16_f32 v71, v72, v73
	v_cvt_pk_bf16_f32 v72, v66, v67
	v_add_u32_e32 v66, 0x80, v148
	v_mad_i64_i32 v[146:147], s[18:19], v148, s74, v[144:145]
	v_cvt_pk_bf16_f32 v110, v110, v111
	v_cvt_pk_bf16_f32 v111, v112, v113
	v_cvt_pk_bf16_f32 v112, v106, v107
	v_cvt_pk_bf16_f32 v113, v108, v109
	v_or_b32_e32 v106, 16, v148
	v_mad_i64_i32 v[66:67], s[18:19], v66, s74, v[144:145]
	v_cvt_pk_bf16_f32 v46, v46, v47
	v_cvt_pk_bf16_f32 v47, v48, v49
	v_cvt_pk_bf16_f32 v48, v42, v43
	v_cvt_pk_bf16_f32 v49, v44, v45
	v_add_u32_e32 v42, 0x90, v148
	global_store_dwordx4 v[146:147], v[110:113], off offset:256
	v_cvt_pk_bf16_f32 v94, v94, v95
	v_cvt_pk_bf16_f32 v95, v96, v97
	v_mad_i64_i32 v[110:111], s[18:19], v106, s74, v[144:145]
	v_cvt_pk_bf16_f32 v96, v90, v91
	v_cvt_pk_bf16_f32 v97, v92, v93
	v_or_b32_e32 v90, 32, v148
	global_store_dwordx4 v[66:67], v[46:49], off offset:256
	v_cvt_pk_bf16_f32 v30, v30, v31
	v_cvt_pk_bf16_f32 v31, v32, v33
	v_mad_i64_i32 v[46:47], s[18:19], v42, s74, v[144:145]
	v_cvt_pk_bf16_f32 v32, v26, v27
	v_cvt_pk_bf16_f32 v33, v28, v29
	v_add_u32_e32 v26, 0xa0, v148
	global_store_dwordx4 v[110:111], v[94:97], off offset:256
	v_cvt_pk_bf16_f32 v78, v78, v79
	v_cvt_pk_bf16_f32 v79, v80, v81
	v_mad_i64_i32 v[94:95], s[18:19], v90, s74, v[144:145]
	v_cvt_pk_bf16_f32 v80, v74, v75
	v_cvt_pk_bf16_f32 v81, v76, v77
	v_or_b32_e32 v74, 48, v148
	global_store_dwordx4 v[46:47], v[30:33], off offset:256
	v_cvt_pk_bf16_f32 v14, v14, v15
	v_cvt_pk_bf16_f32 v15, v16, v17
	v_mad_i64_i32 v[30:31], s[18:19], v26, s74, v[144:145]
	v_cvt_pk_bf16_f32 v16, v10, v11
	v_cvt_pk_bf16_f32 v17, v12, v13
	v_add_u32_e32 v10, 0xb0, v148
	global_store_dwordx4 v[94:95], v[78:81], off offset:256
	global_store_dwordx4 v[30:31], v[14:17], off offset:256
	v_cvt_pk_bf16_f32 v126, v126, v127
	v_mad_i64_i32 v[78:79], s[18:19], v74, s74, v[144:145]
	v_mad_i64_i32 v[14:15], s[18:19], v10, s74, v[144:145]
	v_cvt_pk_bf16_f32 v127, v128, v129
	v_cvt_pk_bf16_f32 v128, v122, v123
	v_cvt_pk_bf16_f32 v129, v124, v125
	v_cvt_pk_bf16_f32 v106, v118, v119
	v_cvt_pk_bf16_f32 v107, v120, v121
	v_cvt_pk_bf16_f32 v108, v114, v115
	v_cvt_pk_bf16_f32 v109, v116, v117
	v_cvt_pk_bf16_f32 v90, v102, v103
	v_cvt_pk_bf16_f32 v91, v104, v105
	v_cvt_pk_bf16_f32 v92, v98, v99
	v_cvt_pk_bf16_f32 v93, v100, v101
	v_cvt_pk_bf16_f32 v74, v86, v87
	v_cvt_pk_bf16_f32 v75, v88, v89
	v_cvt_pk_bf16_f32 v76, v82, v83
	v_cvt_pk_bf16_f32 v77, v84, v85
	v_cvt_pk_bf16_f32 v73, v68, v69
	v_cvt_pk_bf16_f32 v62, v62, v63
	v_cvt_pk_bf16_f32 v63, v64, v65
	v_cvt_pk_bf16_f32 v64, v58, v59
	v_cvt_pk_bf16_f32 v65, v60, v61
	v_cvt_pk_bf16_f32 v42, v54, v55
	v_cvt_pk_bf16_f32 v43, v56, v57
	v_cvt_pk_bf16_f32 v44, v50, v51
	v_cvt_pk_bf16_f32 v45, v52, v53
	v_cvt_pk_bf16_f32 v26, v38, v39
	v_cvt_pk_bf16_f32 v27, v40, v41
	v_cvt_pk_bf16_f32 v28, v34, v35
	v_cvt_pk_bf16_f32 v29, v36, v37
	v_cvt_pk_bf16_f32 v10, v22, v23
	v_cvt_pk_bf16_f32 v11, v24, v25
	v_cvt_pk_bf16_f32 v12, v18, v19
	v_cvt_pk_bf16_f32 v13, v20, v21
	v_cvt_pk_bf16_f32 v6, v6, v7
	v_cvt_pk_bf16_f32 v7, v8, v9
	v_cvt_pk_bf16_f32 v8, v2, v3
	v_cvt_pk_bf16_f32 v9, v4, v5
	s_and_b64 vcc, exec, s[40:41]
	s_mov_b32 s43, s8
	s_mov_b32 s2, s10
	s_mov_b64 s[18:19], s[14:15]
	s_mov_b64 s[22:23], s[12:13]
	global_store_dwordx4 v[146:147], v[126:129], off
	global_store_dwordx4 v[110:111], v[106:109], off
	global_store_dwordx4 v[94:95], v[90:93], off
	global_store_dwordx4 v[78:79], v[74:77], off
	global_store_dwordx4 v[78:79], v[70:73], off offset:256
	global_store_dwordx4 v[66:67], v[62:65], off
	global_store_dwordx4 v[46:47], v[42:45], off
	global_store_dwordx4 v[30:31], v[26:29], off
	global_store_dwordx4 v[14:15], v[10:13], off
	global_store_dwordx4 v[14:15], v[6:9], off offset:256
	s_cbranch_vccz .LBB0_669
	s_waitcnt vmcnt(0)
	s_cmpk_gt_u32 s1, 0xff
	s_cbranch_scc1 .LBB0_676
	s_barrier
